# GEMM K-loops: per-phase s_setprio flips removed, no static raise (A/B of the priority-raise step)
# speedup vs baseline: 1.0103x; 1.0009x over previous
.LBB0_196:
	s_ashr_i32 s9, s8, 31
	v_cmp_lt_i64_e32 vcc, s[10:11], v[140:141]
	s_lshl_b64 s[10:11], s[8:9], 20
	v_readlane_b32 s52, v254, 21
	v_readlane_b32 s53, v254, 22
	s_add_u32 s10, s52, s10
	s_addc_u32 s11, s53, s11
	s_and_b64 s[12:13], vcc, exec
	s_cselect_b32 s5, s11, s17
	s_cselect_b32 s9, s10, s16
	s_ashr_i32 s7, s6, 31
	s_lshl_b64 s[12:13], s[6:7], 20
	s_add_u32 s12, s48, s12
	s_addc_u32 s13, s49, s13
	s_and_b64 s[20:21], vcc, exec
	s_cselect_b32 s7, s13, s19
	s_cselect_b32 s15, s12, s18
	s_add_u32 s16, s16, 0x80080
	s_addc_u32 s17, s17, 0
	s_add_u32 s76, s18, 0x100
	v_mov_b32_e32 v0, 0
	s_addc_u32 s77, s19, 0
	s_mov_b32 s78, -2
	v_mov_b32_e32 v1, v0
	v_mov_b32_e32 v2, v0
	v_mov_b32_e32 v3, v0
	v_mov_b32_e32 v4, v0
	v_mov_b32_e32 v5, v0
	v_mov_b32_e32 v6, v0
	v_mov_b32_e32 v7, v0
	v_mov_b32_e32 v16, v0
	v_mov_b32_e32 v17, v0
	v_mov_b32_e32 v18, v0
	v_mov_b32_e32 v19, v0
	v_mov_b32_e32 v20, v0
	v_mov_b32_e32 v21, v0
	v_mov_b32_e32 v22, v0
	v_mov_b32_e32 v23, v0
	v_mov_b32_e32 v32, v0
	v_mov_b32_e32 v33, v0
	v_mov_b32_e32 v34, v0
	v_mov_b32_e32 v35, v0
	v_mov_b32_e32 v36, v0
	v_mov_b32_e32 v37, v0
	v_mov_b32_e32 v38, v0
	v_mov_b32_e32 v39, v0
	v_mov_b32_e32 v48, v0
	v_mov_b32_e32 v49, v0
	v_mov_b32_e32 v50, v0
	v_mov_b32_e32 v51, v0
	v_mov_b32_e32 v52, v0
	v_mov_b32_e32 v53, v0
	v_mov_b32_e32 v54, v0
	v_mov_b32_e32 v55, v0
	v_mov_b32_e32 v8, v0
	v_mov_b32_e32 v9, v0
	v_mov_b32_e32 v10, v0
	v_mov_b32_e32 v11, v0
	v_mov_b32_e32 v12, v0
	v_mov_b32_e32 v13, v0
	v_mov_b32_e32 v14, v0
	v_mov_b32_e32 v15, v0
	v_mov_b32_e32 v24, v0
	v_mov_b32_e32 v25, v0
	v_mov_b32_e32 v26, v0
	v_mov_b32_e32 v27, v0
	v_mov_b32_e32 v28, v0
	v_mov_b32_e32 v29, v0
	v_mov_b32_e32 v30, v0
	v_mov_b32_e32 v31, v0
	v_mov_b32_e32 v40, v0
	v_mov_b32_e32 v41, v0
	v_mov_b32_e32 v42, v0
	v_mov_b32_e32 v43, v0
	v_mov_b32_e32 v44, v0
	v_mov_b32_e32 v45, v0
	v_mov_b32_e32 v46, v0
	v_mov_b32_e32 v47, v0
	v_mov_b32_e32 v56, v0
	v_mov_b32_e32 v57, v0
	v_mov_b32_e32 v58, v0
	v_mov_b32_e32 v59, v0
	v_mov_b32_e32 v60, v0
	v_mov_b32_e32 v61, v0
	v_mov_b32_e32 v62, v0
	v_mov_b32_e32 v63, v0
	v_mov_b32_e32 v64, v0
	v_mov_b32_e32 v65, v0
	v_mov_b32_e32 v66, v0
	v_mov_b32_e32 v67, v0
	v_mov_b32_e32 v68, v0
	v_mov_b32_e32 v69, v0
	v_mov_b32_e32 v70, v0
	v_mov_b32_e32 v71, v0
	v_mov_b32_e32 v80, v0
	v_mov_b32_e32 v81, v0
	v_mov_b32_e32 v82, v0
	v_mov_b32_e32 v83, v0
	v_mov_b32_e32 v84, v0
	v_mov_b32_e32 v85, v0
	v_mov_b32_e32 v86, v0
	v_mov_b32_e32 v87, v0
	v_mov_b32_e32 v96, v0
	v_mov_b32_e32 v97, v0
	v_mov_b32_e32 v98, v0
	v_mov_b32_e32 v99, v0
	v_mov_b32_e32 v100, v0
	v_mov_b32_e32 v101, v0
	v_mov_b32_e32 v102, v0
	v_mov_b32_e32 v103, v0
	v_mov_b32_e32 v112, v0
	v_mov_b32_e32 v113, v0
	v_mov_b32_e32 v114, v0
	v_mov_b32_e32 v115, v0
	v_mov_b32_e32 v116, v0
	v_mov_b32_e32 v117, v0
	v_mov_b32_e32 v118, v0
	v_mov_b32_e32 v119, v0
	v_mov_b32_e32 v72, v0
	v_mov_b32_e32 v73, v0
	v_mov_b32_e32 v74, v0
	v_mov_b32_e32 v75, v0
	v_mov_b32_e32 v76, v0
	v_mov_b32_e32 v77, v0
	v_mov_b32_e32 v78, v0
	v_mov_b32_e32 v79, v0
	v_mov_b32_e32 v88, v0
	v_mov_b32_e32 v89, v0
	v_mov_b32_e32 v90, v0
	v_mov_b32_e32 v91, v0
	v_mov_b32_e32 v92, v0
	v_mov_b32_e32 v93, v0
	v_mov_b32_e32 v94, v0
	v_mov_b32_e32 v95, v0
	v_mov_b32_e32 v104, v0
	v_mov_b32_e32 v105, v0
	v_mov_b32_e32 v106, v0
	v_mov_b32_e32 v107, v0
	v_mov_b32_e32 v108, v0
	v_mov_b32_e32 v109, v0
	v_mov_b32_e32 v110, v0
	v_mov_b32_e32 v111, v0
	v_mov_b32_e32 v120, v0
	v_mov_b32_e32 v121, v0
	v_mov_b32_e32 v122, v0
	v_mov_b32_e32 v123, v0
	v_mov_b32_e32 v124, v0
	v_mov_b32_e32 v125, v0
	v_mov_b32_e32 v126, v0
	v_mov_b32_e32 v127, v0
	v_readlane_b32 s54, v254, 23
	v_readlane_b32 s55, v254, 24
	v_readlane_b32 s56, v254, 25
	v_readlane_b32 s57, v254, 26
	v_readlane_b32 s58, v254, 27
	v_readlane_b32 s59, v254, 28
	v_readlane_b32 s60, v254, 29
	v_readlane_b32 s61, v254, 30
	v_readlane_b32 s62, v254, 31
	v_readlane_b32 s63, v254, 32
	v_readlane_b32 s64, v254, 33
	v_readlane_b32 s65, v254, 34
	v_readlane_b32 s66, v254, 35
	v_readlane_b32 s67, v254, 36
.LBB0_197:
	ds_read_b128 v[144:147], v151
	ds_read_b128 v[154:157], v151 offset:1024
	ds_read_b128 v[158:161], v151 offset:2048
	ds_read_b128 v[162:165], v151 offset:3072
	s_add_u32 s18, s16, 0xfff80080
	s_addc_u32 s19, s17, -1
	s_cmp_eq_u32 s78, 28
	s_cselect_b32 s21, s5, s19
	s_cselect_b32 s20, s9, s18
	s_cselect_b32 s19, s7, s77
	s_cselect_b32 s18, s15, s76
	v_lshl_add_u64 v[198:199], s[16:17], 0, v[136:137]
	s_add_i32 m0, s24, 0xc000
	ds_read_b128 v[166:169], v152
	ds_read_b128 v[170:173], v152 offset:1024
	ds_read_b128 v[174:177], v152 offset:2048
	ds_read_b128 v[178:181], v152 offset:3072
	ds_read_b128 v[182:185], v152 offset:4096
	ds_read_b128 v[186:189], v152 offset:5120
	ds_read_b128 v[190:193], v152 offset:6144
	ds_read_b128 v[194:197], v152 offset:7168
	global_load_lds_dwordx4 v[198:199], off
	v_lshl_add_u64 v[198:199], s[16:17], 0, v[138:139]
	s_add_i32 m0, s24, 0xe000
	s_nop 0
	global_load_lds_dwordx4 v[198:199], off
	s_waitcnt lgkmcnt(8)
	s_barrier
	s_waitcnt lgkmcnt(0)
	s_waitcnt lgkmcnt(0)
	v_mfma_f32_16x16x32_f16 v[124:127], v[144:147], v[166:169], v[124:127]
	v_mfma_f32_16x16x32_f16 v[120:123], v[158:161], v[166:169], v[120:123]
	v_mfma_f32_16x16x32_f16 v[108:111], v[144:147], v[174:177], v[108:111]
	v_mfma_f32_16x16x32_f16 v[104:107], v[158:161], v[174:177], v[104:107]
	v_mfma_f32_16x16x32_f16 v[92:95], v[144:147], v[182:185], v[92:95]
	v_mfma_f32_16x16x32_f16 v[88:91], v[158:161], v[182:185], v[88:91]
	v_mfma_f32_16x16x32_f16 v[76:79], v[144:147], v[190:193], v[76:79]
	v_mfma_f32_16x16x32_f16 v[72:75], v[158:161], v[190:193], v[72:75]
	v_mfma_f32_16x16x32_f16 v[124:127], v[154:157], v[170:173], v[124:127]
	v_mfma_f32_16x16x32_f16 v[120:123], v[162:165], v[170:173], v[120:123]
	v_mfma_f32_16x16x32_f16 v[108:111], v[154:157], v[178:181], v[108:111]
	v_mfma_f32_16x16x32_f16 v[104:107], v[162:165], v[178:181], v[104:107]
	v_mfma_f32_16x16x32_f16 v[92:95], v[154:157], v[186:189], v[92:95]
	v_mfma_f32_16x16x32_f16 v[88:91], v[162:165], v[186:189], v[88:91]
	v_mfma_f32_16x16x32_f16 v[76:79], v[154:157], v[194:197], v[76:79]
	v_mfma_f32_16x16x32_f16 v[72:75], v[162:165], v[194:197], v[72:75]
	s_barrier
	s_add_i32 s79, s68, s23
	v_lshl_add_u64 v[214:215], s[18:19], 0, v[130:131]
	s_mov_b32 m0, s79
	ds_read_b128 v[198:201], v153
	ds_read_b128 v[202:205], v153 offset:1024
	ds_read_b128 v[206:209], v153 offset:2048
	ds_read_b128 v[210:213], v153 offset:3072
	global_load_lds_dwordx4 v[214:215], off
	v_lshl_add_u64 v[216:217], s[18:19], 0, v[134:135]
	s_add_i32 m0, s79, 0x2000
	s_nop 0
	global_load_lds_dwordx4 v[216:217], off
	s_barrier
	s_waitcnt lgkmcnt(0)
	s_waitcnt lgkmcnt(0)
	v_mfma_f32_16x16x32_f16 v[116:119], v[198:201], v[166:169], v[116:119]
	v_mfma_f32_16x16x32_f16 v[112:115], v[206:209], v[166:169], v[112:115]
	v_mfma_f32_16x16x32_f16 v[100:103], v[198:201], v[174:177], v[100:103]
	v_mfma_f32_16x16x32_f16 v[96:99], v[206:209], v[174:177], v[96:99]
	v_mfma_f32_16x16x32_f16 v[84:87], v[198:201], v[182:185], v[84:87]
	v_mfma_f32_16x16x32_f16 v[80:83], v[206:209], v[182:185], v[80:83]
	v_mfma_f32_16x16x32_f16 v[68:71], v[198:201], v[190:193], v[68:71]
	v_mfma_f32_16x16x32_f16 v[64:67], v[206:209], v[190:193], v[64:67]
	v_mfma_f32_16x16x32_f16 v[116:119], v[202:205], v[170:173], v[116:119]
	v_mfma_f32_16x16x32_f16 v[112:115], v[210:213], v[170:173], v[112:115]
	v_mfma_f32_16x16x32_f16 v[100:103], v[202:205], v[178:181], v[100:103]
	v_mfma_f32_16x16x32_f16 v[96:99], v[210:213], v[178:181], v[96:99]
	v_mfma_f32_16x16x32_f16 v[84:87], v[202:205], v[186:189], v[84:87]
	v_mfma_f32_16x16x32_f16 v[80:83], v[210:213], v[186:189], v[80:83]
	v_mfma_f32_16x16x32_f16 v[68:71], v[202:205], v[194:197], v[68:71]
	v_mfma_f32_16x16x32_f16 v[64:67], v[210:213], v[194:197], v[64:67]
	s_mov_b32 m0, s24
	v_lshl_add_u64 v[218:219], s[20:21], 0, v[128:129]
	s_barrier
	ds_read_b128 v[166:169], v152 offset:16384
	ds_read_b128 v[170:173], v152 offset:17408
	ds_read_b128 v[174:177], v152 offset:18432
	ds_read_b128 v[178:181], v152 offset:19456
	ds_read_b128 v[182:185], v152 offset:20480
	ds_read_b128 v[186:189], v152 offset:21504
	ds_read_b128 v[190:193], v152 offset:22528
	ds_read_b128 v[194:197], v152 offset:23552
	global_load_lds_dwordx4 v[218:219], off
	v_lshl_add_u64 v[220:221], s[20:21], 0, v[132:133]
	s_mov_b32 m0, s25
	s_nop 0
	global_load_lds_dwordx4 v[220:221], off
	s_barrier
	s_waitcnt lgkmcnt(0)
	s_waitcnt lgkmcnt(0)
	v_mfma_f32_16x16x32_f16 v[60:63], v[144:147], v[166:169], v[60:63]
	v_mfma_f32_16x16x32_f16 v[56:59], v[158:161], v[166:169], v[56:59]
	v_mfma_f32_16x16x32_f16 v[44:47], v[144:147], v[174:177], v[44:47]
	v_mfma_f32_16x16x32_f16 v[40:43], v[158:161], v[174:177], v[40:43]
	v_mfma_f32_16x16x32_f16 v[28:31], v[144:147], v[182:185], v[28:31]
	v_mfma_f32_16x16x32_f16 v[24:27], v[158:161], v[182:185], v[24:27]
	v_mfma_f32_16x16x32_f16 v[12:15], v[144:147], v[190:193], v[12:15]
	v_mfma_f32_16x16x32_f16 v[8:11], v[158:161], v[190:193], v[8:11]
	v_mfma_f32_16x16x32_f16 v[60:63], v[154:157], v[170:173], v[60:63]
	v_mfma_f32_16x16x32_f16 v[56:59], v[162:165], v[170:173], v[56:59]
	v_mfma_f32_16x16x32_f16 v[44:47], v[154:157], v[178:181], v[44:47]
	v_mfma_f32_16x16x32_f16 v[40:43], v[162:165], v[178:181], v[40:43]
	v_mfma_f32_16x16x32_f16 v[28:31], v[154:157], v[186:189], v[28:31]
	v_mfma_f32_16x16x32_f16 v[24:27], v[162:165], v[186:189], v[24:27]
	v_mfma_f32_16x16x32_f16 v[12:15], v[154:157], v[194:197], v[12:15]
	v_mfma_f32_16x16x32_f16 v[8:11], v[162:165], v[194:197], v[8:11]
	s_barrier
	s_add_u32 s80, s18, 0x80000
	s_addc_u32 s81, s19, 0
	s_add_i32 s79, s69, s23
	v_lshl_add_u64 v[144:145], s[80:81], 0, v[130:131]
	s_mov_b32 m0, s79
	s_nop 0
	global_load_lds_dwordx4 v[144:145], off
	v_lshl_add_u64 v[144:145], s[80:81], 0, v[134:135]
	s_add_i32 m0, s79, 0x2000
	s_nop 0
	global_load_lds_dwordx4 v[144:145], off
	s_waitcnt vmcnt(6)
	s_barrier
	v_mfma_f32_16x16x32_f16 v[52:55], v[198:201], v[166:169], v[52:55]
	v_mfma_f32_16x16x32_f16 v[48:51], v[206:209], v[166:169], v[48:51]
	v_mfma_f32_16x16x32_f16 v[36:39], v[198:201], v[174:177], v[36:39]
	v_mfma_f32_16x16x32_f16 v[32:35], v[206:209], v[174:177], v[32:35]
	v_mfma_f32_16x16x32_f16 v[20:23], v[198:201], v[182:185], v[20:23]
	v_mfma_f32_16x16x32_f16 v[16:19], v[206:209], v[182:185], v[16:19]
	v_mfma_f32_16x16x32_f16 v[4:7], v[198:201], v[190:193], v[4:7]
	v_mfma_f32_16x16x32_f16 v[0:3], v[206:209], v[190:193], v[0:3]
	v_mfma_f32_16x16x32_f16 v[52:55], v[202:205], v[170:173], v[52:55]
	v_mfma_f32_16x16x32_f16 v[48:51], v[210:213], v[170:173], v[48:51]
	v_mfma_f32_16x16x32_f16 v[36:39], v[202:205], v[178:181], v[36:39]
	v_mfma_f32_16x16x32_f16 v[32:35], v[210:213], v[178:181], v[32:35]
	v_mfma_f32_16x16x32_f16 v[20:23], v[202:205], v[186:189], v[20:23]
	v_mfma_f32_16x16x32_f16 v[16:19], v[210:213], v[186:189], v[16:19]
	v_mfma_f32_16x16x32_f16 v[4:7], v[202:205], v[194:197], v[4:7]
	v_mfma_f32_16x16x32_f16 v[0:3], v[210:213], v[194:197], v[0:3]
	s_add_i32 s79, 0, 0x18000
	v_add_u32_e32 v162, s79, v149
	s_barrier
	ds_read_b128 v[144:147], v162
	ds_read_b128 v[154:157], v162 offset:1024
	ds_read_b128 v[158:161], v162 offset:2048
	ds_read_b128 v[162:165], v162 offset:3072
	s_add_u32 s20, s20, 0x80000
	s_addc_u32 s21, s21, 0
	s_mov_b32 m0, s26
	v_lshl_add_u64 v[198:199], s[20:21], 0, v[128:129]
	ds_read_b128 v[166:169], v152 offset:32768
	ds_read_b128 v[170:173], v152 offset:33792
	ds_read_b128 v[174:177], v152 offset:34816
	ds_read_b128 v[178:181], v152 offset:35840
	ds_read_b128 v[182:185], v152 offset:36864
	ds_read_b128 v[186:189], v152 offset:37888
	ds_read_b128 v[190:193], v152 offset:38912
	ds_read_b128 v[194:197], v152 offset:39936
	global_load_lds_dwordx4 v[198:199], off
	v_lshl_add_u64 v[198:199], s[20:21], 0, v[132:133]
	s_mov_b32 m0, s27
	s_nop 0
	global_load_lds_dwordx4 v[198:199], off
	s_waitcnt lgkmcnt(8)
	s_barrier
	s_waitcnt lgkmcnt(0)
	s_waitcnt lgkmcnt(0)
	v_mfma_f32_16x16x32_f16 v[124:127], v[144:147], v[166:169], v[124:127]
	v_mfma_f32_16x16x32_f16 v[120:123], v[158:161], v[166:169], v[120:123]
	v_mfma_f32_16x16x32_f16 v[108:111], v[144:147], v[174:177], v[108:111]
	v_mfma_f32_16x16x32_f16 v[104:107], v[158:161], v[174:177], v[104:107]
	v_mfma_f32_16x16x32_f16 v[92:95], v[144:147], v[182:185], v[92:95]
	v_mfma_f32_16x16x32_f16 v[88:91], v[158:161], v[182:185], v[88:91]
	v_mfma_f32_16x16x32_f16 v[76:79], v[144:147], v[190:193], v[76:79]
	v_mfma_f32_16x16x32_f16 v[72:75], v[158:161], v[190:193], v[72:75]
	v_mfma_f32_16x16x32_f16 v[124:127], v[154:157], v[170:173], v[124:127]
	v_mfma_f32_16x16x32_f16 v[120:123], v[162:165], v[170:173], v[120:123]
	v_mfma_f32_16x16x32_f16 v[108:111], v[154:157], v[178:181], v[108:111]
	v_mfma_f32_16x16x32_f16 v[104:107], v[162:165], v[178:181], v[104:107]
	v_mfma_f32_16x16x32_f16 v[92:95], v[154:157], v[186:189], v[92:95]
	v_mfma_f32_16x16x32_f16 v[88:91], v[162:165], v[186:189], v[88:91]
	v_mfma_f32_16x16x32_f16 v[76:79], v[154:157], v[194:197], v[76:79]
	v_mfma_f32_16x16x32_f16 v[72:75], v[162:165], v[194:197], v[72:75]
	s_barrier
	s_add_i32 s20, 0, 0x1c000
	s_add_i32 s21, s79, s23
	v_add_u32_e32 v210, s20, v149
	v_lshl_add_u64 v[214:215], v[214:215], 0, s[0:1]
	s_mov_b32 m0, s21
	ds_read_b128 v[198:201], v210
	ds_read_b128 v[202:205], v210 offset:1024
	ds_read_b128 v[206:209], v210 offset:2048
	ds_read_b128 v[210:213], v210 offset:3072
	global_load_lds_dwordx4 v[214:215], off
	v_lshl_add_u64 v[214:215], v[216:217], 0, s[0:1]
	s_add_i32 m0, s21, 0x2000
	s_nop 0
	global_load_lds_dwordx4 v[214:215], off
	s_barrier
	s_waitcnt lgkmcnt(0)
	s_waitcnt lgkmcnt(0)
	v_mfma_f32_16x16x32_f16 v[116:119], v[198:201], v[166:169], v[116:119]
	v_mfma_f32_16x16x32_f16 v[112:115], v[206:209], v[166:169], v[112:115]
	v_mfma_f32_16x16x32_f16 v[100:103], v[198:201], v[174:177], v[100:103]
	v_mfma_f32_16x16x32_f16 v[96:99], v[206:209], v[174:177], v[96:99]
	v_mfma_f32_16x16x32_f16 v[84:87], v[198:201], v[182:185], v[84:87]
	v_mfma_f32_16x16x32_f16 v[80:83], v[206:209], v[182:185], v[80:83]
	v_mfma_f32_16x16x32_f16 v[68:71], v[198:201], v[190:193], v[68:71]
	v_mfma_f32_16x16x32_f16 v[64:67], v[206:209], v[190:193], v[64:67]
	v_mfma_f32_16x16x32_f16 v[116:119], v[202:205], v[170:173], v[116:119]
	v_mfma_f32_16x16x32_f16 v[112:115], v[210:213], v[170:173], v[112:115]
	v_mfma_f32_16x16x32_f16 v[100:103], v[202:205], v[178:181], v[100:103]
	v_mfma_f32_16x16x32_f16 v[96:99], v[210:213], v[178:181], v[96:99]
	v_mfma_f32_16x16x32_f16 v[84:87], v[202:205], v[186:189], v[84:87]
	v_mfma_f32_16x16x32_f16 v[80:83], v[210:213], v[186:189], v[80:83]
	v_mfma_f32_16x16x32_f16 v[68:71], v[202:205], v[194:197], v[68:71]
	v_mfma_f32_16x16x32_f16 v[64:67], v[210:213], v[194:197], v[64:67]
	s_mov_b32 m0, s29
	v_lshl_add_u64 v[214:215], v[218:219], 0, s[0:1]
	s_barrier
	ds_read_b128 v[166:169], v152 offset:49152
	ds_read_b128 v[170:173], v152 offset:50176
	ds_read_b128 v[174:177], v152 offset:51200
	ds_read_b128 v[178:181], v152 offset:52224
	ds_read_b128 v[182:185], v152 offset:53248
	ds_read_b128 v[186:189], v152 offset:54272
	ds_read_b128 v[190:193], v152 offset:55296
	ds_read_b128 v[194:197], v152 offset:56320
	global_load_lds_dwordx4 v[214:215], off
	v_lshl_add_u64 v[214:215], v[220:221], 0, s[0:1]
	s_mov_b32 m0, s30
	s_nop 0
	global_load_lds_dwordx4 v[214:215], off
	s_barrier
	s_waitcnt lgkmcnt(0)
	s_waitcnt lgkmcnt(0)
	v_mfma_f32_16x16x32_f16 v[60:63], v[144:147], v[166:169], v[60:63]
	v_mfma_f32_16x16x32_f16 v[56:59], v[158:161], v[166:169], v[56:59]
	v_mfma_f32_16x16x32_f16 v[44:47], v[144:147], v[174:177], v[44:47]
	v_mfma_f32_16x16x32_f16 v[40:43], v[158:161], v[174:177], v[40:43]
	v_mfma_f32_16x16x32_f16 v[28:31], v[144:147], v[182:185], v[28:31]
	v_mfma_f32_16x16x32_f16 v[24:27], v[158:161], v[182:185], v[24:27]
	v_mfma_f32_16x16x32_f16 v[12:15], v[144:147], v[190:193], v[12:15]
	v_mfma_f32_16x16x32_f16 v[8:11], v[158:161], v[190:193], v[8:11]
	v_mfma_f32_16x16x32_f16 v[60:63], v[154:157], v[170:173], v[60:63]
	v_mfma_f32_16x16x32_f16 v[56:59], v[162:165], v[170:173], v[56:59]
	v_mfma_f32_16x16x32_f16 v[44:47], v[154:157], v[178:181], v[44:47]
	v_mfma_f32_16x16x32_f16 v[40:43], v[162:165], v[178:181], v[40:43]
	v_mfma_f32_16x16x32_f16 v[28:31], v[154:157], v[186:189], v[28:31]
	v_mfma_f32_16x16x32_f16 v[24:27], v[162:165], v[186:189], v[24:27]
	v_mfma_f32_16x16x32_f16 v[12:15], v[154:157], v[194:197], v[12:15]
	v_mfma_f32_16x16x32_f16 v[8:11], v[162:165], v[194:197], v[8:11]
	s_barrier
	s_add_u32 s18, s18, 0x80080
	s_addc_u32 s19, s19, 0
	s_add_i32 s20, s20, s23
	v_lshl_add_u64 v[144:145], s[18:19], 0, v[130:131]
	s_mov_b32 m0, s20
	s_nop 0
	global_load_lds_dwordx4 v[144:145], off
	v_lshl_add_u64 v[144:145], s[18:19], 0, v[134:135]
	s_add_i32 m0, s20, 0x2000
	s_nop 0
	global_load_lds_dwordx4 v[144:145], off
	s_waitcnt vmcnt(6)
	s_barrier
	v_mfma_f32_16x16x32_f16 v[52:55], v[198:201], v[166:169], v[52:55]
	v_mfma_f32_16x16x32_f16 v[48:51], v[206:209], v[166:169], v[48:51]
	v_mfma_f32_16x16x32_f16 v[36:39], v[198:201], v[174:177], v[36:39]
	v_mfma_f32_16x16x32_f16 v[32:35], v[206:209], v[174:177], v[32:35]
	v_mfma_f32_16x16x32_f16 v[20:23], v[198:201], v[182:185], v[20:23]
	v_mfma_f32_16x16x32_f16 v[16:19], v[206:209], v[182:185], v[16:19]
	v_mfma_f32_16x16x32_f16 v[4:7], v[198:201], v[190:193], v[4:7]
	v_mfma_f32_16x16x32_f16 v[0:3], v[206:209], v[190:193], v[0:3]
	v_mfma_f32_16x16x32_f16 v[52:55], v[202:205], v[170:173], v[52:55]
	v_mfma_f32_16x16x32_f16 v[48:51], v[210:213], v[170:173], v[48:51]
	v_mfma_f32_16x16x32_f16 v[36:39], v[202:205], v[178:181], v[36:39]
	v_mfma_f32_16x16x32_f16 v[32:35], v[210:213], v[178:181], v[32:35]
	v_mfma_f32_16x16x32_f16 v[20:23], v[202:205], v[186:189], v[20:23]
	v_mfma_f32_16x16x32_f16 v[16:19], v[210:213], v[186:189], v[16:19]
	v_mfma_f32_16x16x32_f16 v[4:7], v[202:205], v[194:197], v[4:7]
	v_mfma_f32_16x16x32_f16 v[0:3], v[210:213], v[194:197], v[0:3]
	s_add_i32 s78, s78, 2
	s_add_u32 s16, s16, 0x100
	s_addc_u32 s17, s17, 0
	s_add_u32 s76, s76, 0x100
	s_addc_u32 s77, s77, 0
	s_cmp_gt_u32 s78, 29
	s_barrier
	s_cbranch_scc0 .LBB0_197
	s_setprio 0
	v_readlane_b32 s52, v254, 21
	v_readlane_b32 s54, v254, 23
	v_readlane_b32 s55, v254, 24
	v_lshl_add_u32 v154, s14, 8, v148
	v_lshl_or_b32 v144, s4, 8, v150
	v_mov_b64_e32 v[146:147], s[54:55]
	v_mad_i64_i32 v[146:147], s[4:5], v154, s70, v[146:147]
	v_cmp_gt_i32_e32 vcc, s71, v144
	v_ashrrev_i32_e32 v145, 31, v144
	v_readlane_b32 s53, v254, 22
	v_readlane_b32 s56, v254, 25
	v_readlane_b32 s57, v254, 26
	v_readlane_b32 s58, v254, 27
	v_readlane_b32 s59, v254, 28
	v_readlane_b32 s60, v254, 29
	v_readlane_b32 s61, v254, 30
	v_readlane_b32 s62, v254, 31
	v_readlane_b32 s63, v254, 32
	v_readlane_b32 s64, v254, 33
	v_readlane_b32 s65, v254, 34
	v_readlane_b32 s66, v254, 35
	v_readlane_b32 s67, v254, 36
	s_and_saveexec_b64 s[4:5], vcc
	s_cbranch_execz .LBB0_200
	v_cvt_pk_f16_f32 v123, v122, v123
	v_cvt_pk_f16_f32 v122, v120, v121
	v_cvt_pk_f16_f32 v121, v126, v127
	v_cvt_pk_f16_f32 v120, v124, v125
	v_lshl_add_u64 v[124:125], v[144:145], 1, v[146:147]
	global_store_dwordx4 v[124:125], v[120:123], off

.LBB0_646:
	s_ashr_i32 s9, s8, 31
	v_cmp_lt_i64_e32 vcc, s[10:11], v[216:217]
	s_lshl_b64 s[10:11], s[8:9], 20
	v_readlane_b32 s52, v254, 21
	v_readlane_b32 s53, v254, 22
	s_add_u32 s10, s52, s10
	s_addc_u32 s11, s53, s11
	s_and_b64 s[12:13], vcc, exec
	s_cselect_b32 s9, s11, s17
	s_cselect_b32 s31, s10, s16
	s_ashr_i32 s7, s6, 31
	s_lshl_b64 s[12:13], s[6:7], 20
	s_add_u32 s12, s50, s12
	s_addc_u32 s13, s51, s13
	s_and_b64 s[20:21], vcc, exec
	s_cselect_b32 s7, s13, s19
	s_cselect_b32 s77, s12, s18
	s_add_u32 s16, s16, 0x80080
	s_addc_u32 s17, s17, 0
	s_add_u32 s78, s18, 0x100
	v_mov_b32_e32 v0, 0
	s_addc_u32 s79, s19, 0
	s_mov_b32 s80, -2
	v_mov_b32_e32 v1, v0
	v_mov_b32_e32 v2, v0
	v_mov_b32_e32 v3, v0
	v_mov_b32_e32 v4, v0
	v_mov_b32_e32 v5, v0
	v_mov_b32_e32 v6, v0
	v_mov_b32_e32 v7, v0
	v_mov_b32_e32 v16, v0
	v_mov_b32_e32 v17, v0
	v_mov_b32_e32 v18, v0
	v_mov_b32_e32 v19, v0
	v_mov_b32_e32 v20, v0
	v_mov_b32_e32 v21, v0
	v_mov_b32_e32 v22, v0
	v_mov_b32_e32 v23, v0
	v_mov_b32_e32 v32, v0
	v_mov_b32_e32 v33, v0
	v_mov_b32_e32 v34, v0
	v_mov_b32_e32 v35, v0
	v_mov_b32_e32 v36, v0
	v_mov_b32_e32 v37, v0
	v_mov_b32_e32 v38, v0
	v_mov_b32_e32 v39, v0
	v_mov_b32_e32 v48, v0
	v_mov_b32_e32 v49, v0
	v_mov_b32_e32 v50, v0
	v_mov_b32_e32 v51, v0
	v_mov_b32_e32 v52, v0
	v_mov_b32_e32 v53, v0
	v_mov_b32_e32 v54, v0
	v_mov_b32_e32 v55, v0
	v_mov_b32_e32 v8, v0
	v_mov_b32_e32 v9, v0
	v_mov_b32_e32 v10, v0
	v_mov_b32_e32 v11, v0
	v_mov_b32_e32 v12, v0
	v_mov_b32_e32 v13, v0
	v_mov_b32_e32 v14, v0
	v_mov_b32_e32 v15, v0
	v_mov_b32_e32 v24, v0
	v_mov_b32_e32 v25, v0
	v_mov_b32_e32 v26, v0
	v_mov_b32_e32 v27, v0
	v_mov_b32_e32 v28, v0
	v_mov_b32_e32 v29, v0
	v_mov_b32_e32 v30, v0
	v_mov_b32_e32 v31, v0
	v_mov_b32_e32 v40, v0
	v_mov_b32_e32 v41, v0
	v_mov_b32_e32 v42, v0
	v_mov_b32_e32 v43, v0
	v_mov_b32_e32 v44, v0
	v_mov_b32_e32 v45, v0
	v_mov_b32_e32 v46, v0
	v_mov_b32_e32 v47, v0
	v_mov_b32_e32 v56, v0
	v_mov_b32_e32 v57, v0
	v_mov_b32_e32 v58, v0
	v_mov_b32_e32 v59, v0
	v_mov_b32_e32 v60, v0
	v_mov_b32_e32 v61, v0
	v_mov_b32_e32 v62, v0
	v_mov_b32_e32 v63, v0
	v_mov_b32_e32 v64, v0
	v_mov_b32_e32 v65, v0
	v_mov_b32_e32 v66, v0
	v_mov_b32_e32 v67, v0
	v_mov_b32_e32 v68, v0
	v_mov_b32_e32 v69, v0
	v_mov_b32_e32 v70, v0
	v_mov_b32_e32 v71, v0
	v_mov_b32_e32 v84, v0
	v_mov_b32_e32 v85, v0
	v_mov_b32_e32 v86, v0
	v_mov_b32_e32 v87, v0
	v_mov_b32_e32 v92, v0
	v_mov_b32_e32 v93, v0
	v_mov_b32_e32 v94, v0
	v_mov_b32_e32 v95, v0
	v_mov_b32_e32 v112, v0
	v_mov_b32_e32 v113, v0
	v_mov_b32_e32 v114, v0
	v_mov_b32_e32 v115, v0
	v_mov_b32_e32 v116, v0
	v_mov_b32_e32 v117, v0
	v_mov_b32_e32 v118, v0
	v_mov_b32_e32 v119, v0
	v_mov_b32_e32 v140, v0
	v_mov_b32_e32 v141, v0
	v_mov_b32_e32 v142, v0
	v_mov_b32_e32 v143, v0
	v_mov_b32_e32 v144, v0
	v_mov_b32_e32 v145, v0
	v_mov_b32_e32 v146, v0
	v_mov_b32_e32 v147, v0
	v_mov_b32_e32 v72, v0
	v_mov_b32_e32 v73, v0
	v_mov_b32_e32 v74, v0
	v_mov_b32_e32 v75, v0
	v_mov_b32_e32 v76, v0
	v_mov_b32_e32 v77, v0
	v_mov_b32_e32 v78, v0
	v_mov_b32_e32 v79, v0
	v_mov_b32_e32 v104, v0
	v_mov_b32_e32 v105, v0
	v_mov_b32_e32 v106, v0
	v_mov_b32_e32 v107, v0
	v_mov_b32_e32 v108, v0
	v_mov_b32_e32 v109, v0
	v_mov_b32_e32 v110, v0
	v_mov_b32_e32 v111, v0
	v_mov_b32_e32 v124, v0
	v_mov_b32_e32 v125, v0
	v_mov_b32_e32 v126, v0
	v_mov_b32_e32 v127, v0
	v_mov_b32_e32 v128, v0
	v_mov_b32_e32 v129, v0
	v_mov_b32_e32 v130, v0
	v_mov_b32_e32 v131, v0
	v_mov_b32_e32 v164, v0
	v_mov_b32_e32 v165, v0
	v_mov_b32_e32 v166, v0
	v_mov_b32_e32 v167, v0
	v_mov_b32_e32 v168, v0
	v_mov_b32_e32 v169, v0
	v_mov_b32_e32 v170, v0
	v_mov_b32_e32 v171, v0
	v_readlane_b32 s54, v254, 23
	v_readlane_b32 s55, v254, 24
	v_readlane_b32 s56, v254, 25
	v_readlane_b32 s57, v254, 26
	v_readlane_b32 s58, v254, 27
	v_readlane_b32 s59, v254, 28
	v_readlane_b32 s60, v254, 29
	v_readlane_b32 s61, v254, 30
	v_readlane_b32 s62, v254, 31
	v_readlane_b32 s63, v254, 32
	v_readlane_b32 s64, v254, 33
	v_readlane_b32 s65, v254, 34
	v_readlane_b32 s66, v254, 35
	v_readlane_b32 s67, v254, 36
.LBB0_647:
	ds_read_b128 v[80:83], v243
	ds_read_b128 v[88:91], v243 offset:1024
	ds_read_b128 v[96:99], v243 offset:2048
	ds_read_b128 v[100:103], v243 offset:3072
	s_add_u32 s18, s16, 0xfff80080
	s_addc_u32 s19, s17, -1
	s_cmp_eq_u32 s80, 28
	s_cselect_b32 s21, s9, s19
	s_cselect_b32 s20, s31, s18
	s_cselect_b32 s19, s7, s79
	s_cselect_b32 s18, s77, s78
	v_lshl_add_u64 v[176:177], s[16:17], 0, v[212:213]
	s_add_i32 m0, s15, 0xc000
	ds_read_b128 v[120:123], v244
	ds_read_b128 v[132:135], v244 offset:1024
	ds_read_b128 v[136:139], v244 offset:2048
	ds_read_b128 v[148:151], v244 offset:3072
	ds_read_b128 v[152:155], v244 offset:4096
	ds_read_b128 v[156:159], v244 offset:5120
	ds_read_b128 v[160:163], v244 offset:6144
	ds_read_b128 v[172:175], v244 offset:7168
	global_load_lds_dwordx4 v[176:177], off
	v_lshl_add_u64 v[176:177], s[16:17], 0, v[214:215]
	s_add_i32 m0, s15, 0xe000
	s_nop 0
	global_load_lds_dwordx4 v[176:177], off
	s_waitcnt lgkmcnt(8)
	s_barrier
	s_waitcnt lgkmcnt(0)
	s_waitcnt lgkmcnt(0)
	v_mfma_f32_16x16x32_f16 v[168:171], v[80:83], v[120:123], v[168:171]
	v_mfma_f32_16x16x32_f16 v[164:167], v[96:99], v[120:123], v[164:167]
	v_mfma_f32_16x16x32_f16 v[128:131], v[80:83], v[136:139], v[128:131]
	v_mfma_f32_16x16x32_f16 v[124:127], v[96:99], v[136:139], v[124:127]
	v_mfma_f32_16x16x32_f16 v[108:111], v[80:83], v[152:155], v[108:111]
	v_mfma_f32_16x16x32_f16 v[104:107], v[96:99], v[152:155], v[104:107]
	v_mfma_f32_16x16x32_f16 v[76:79], v[80:83], v[160:163], v[76:79]
	v_mfma_f32_16x16x32_f16 v[72:75], v[96:99], v[160:163], v[72:75]
	v_mfma_f32_16x16x32_f16 v[168:171], v[88:91], v[132:135], v[168:171]
	v_mfma_f32_16x16x32_f16 v[164:167], v[100:103], v[132:135], v[164:167]
	v_mfma_f32_16x16x32_f16 v[128:131], v[88:91], v[148:151], v[128:131]
	v_mfma_f32_16x16x32_f16 v[124:127], v[100:103], v[148:151], v[124:127]
	v_mfma_f32_16x16x32_f16 v[108:111], v[88:91], v[156:159], v[108:111]
	v_mfma_f32_16x16x32_f16 v[104:107], v[100:103], v[156:159], v[104:107]
	v_mfma_f32_16x16x32_f16 v[76:79], v[88:91], v[172:175], v[76:79]
	v_mfma_f32_16x16x32_f16 v[72:75], v[100:103], v[172:175], v[72:75]
	s_barrier
	s_add_i32 s81, s71, s24
	v_lshl_add_u64 v[196:197], s[18:19], 0, v[206:207]
	s_mov_b32 m0, s81
	ds_read_b128 v[176:179], v245
	ds_read_b128 v[180:183], v245 offset:1024
	ds_read_b128 v[184:187], v245 offset:2048
	ds_read_b128 v[188:191], v245 offset:3072
	global_load_lds_dwordx4 v[196:197], off
	v_lshl_add_u64 v[198:199], s[18:19], 0, v[210:211]
	s_add_i32 m0, s81, 0x2000
	s_nop 0
	global_load_lds_dwordx4 v[198:199], off
	s_barrier
	s_waitcnt lgkmcnt(0)
	s_waitcnt lgkmcnt(0)
	v_mfma_f32_16x16x32_f16 v[144:147], v[176:179], v[120:123], v[144:147]
	v_mfma_f32_16x16x32_f16 v[116:119], v[176:179], v[136:139], v[116:119]
	v_mfma_f32_16x16x32_f16 v[112:115], v[184:187], v[136:139], v[112:115]
	v_mfma_f32_16x16x32_f16 v[92:95], v[176:179], v[152:155], v[92:95]
	v_mfma_f32_16x16x32_f16 v[84:87], v[184:187], v[152:155], v[84:87]
	v_mfma_f32_16x16x32_f16 v[68:71], v[176:179], v[160:163], v[68:71]
	v_mfma_f32_16x16x32_f16 v[64:67], v[184:187], v[160:163], v[64:67]
	v_mfma_f32_16x16x32_f16 v[144:147], v[180:183], v[132:135], v[144:147]
	v_mfma_f32_16x16x32_f16 v[120:123], v[184:187], v[120:123], v[140:143]
	v_mfma_f32_16x16x32_f16 v[116:119], v[180:183], v[148:151], v[116:119]
	v_mfma_f32_16x16x32_f16 v[112:115], v[188:191], v[148:151], v[112:115]
	v_mfma_f32_16x16x32_f16 v[92:95], v[180:183], v[156:159], v[92:95]
	v_mfma_f32_16x16x32_f16 v[84:87], v[188:191], v[156:159], v[84:87]
	v_mfma_f32_16x16x32_f16 v[68:71], v[180:183], v[172:175], v[68:71]
	v_mfma_f32_16x16x32_f16 v[64:67], v[188:191], v[172:175], v[64:67]
	v_mfma_f32_16x16x32_f16 v[120:123], v[188:191], v[132:135], v[120:123]
	s_mov_b32 m0, s15
	v_lshl_add_u64 v[200:201], s[20:21], 0, v[204:205]
	s_barrier
	ds_read_b128 v[132:135], v244 offset:16384
	ds_read_b128 v[136:139], v244 offset:17408
	ds_read_b128 v[140:143], v244 offset:18432
	ds_read_b128 v[148:151], v244 offset:19456
	ds_read_b128 v[152:155], v244 offset:20480
	ds_read_b128 v[156:159], v244 offset:21504
	ds_read_b128 v[160:163], v244 offset:22528
	ds_read_b128 v[172:175], v244 offset:23552
	global_load_lds_dwordx4 v[200:201], off
	v_lshl_add_u64 v[202:203], s[20:21], 0, v[208:209]
	s_mov_b32 m0, s25
	s_nop 0
	global_load_lds_dwordx4 v[202:203], off
	s_barrier
	s_waitcnt lgkmcnt(0)
	s_waitcnt lgkmcnt(0)
	v_mfma_f32_16x16x32_f16 v[60:63], v[80:83], v[132:135], v[60:63]
	v_mfma_f32_16x16x32_f16 v[56:59], v[96:99], v[132:135], v[56:59]
	v_mfma_f32_16x16x32_f16 v[44:47], v[80:83], v[140:143], v[44:47]
	v_mfma_f32_16x16x32_f16 v[40:43], v[96:99], v[140:143], v[40:43]
	v_mfma_f32_16x16x32_f16 v[28:31], v[80:83], v[152:155], v[28:31]
	v_mfma_f32_16x16x32_f16 v[24:27], v[96:99], v[152:155], v[24:27]
	v_mfma_f32_16x16x32_f16 v[12:15], v[80:83], v[160:163], v[12:15]
	v_mfma_f32_16x16x32_f16 v[8:11], v[96:99], v[160:163], v[8:11]
	v_mfma_f32_16x16x32_f16 v[60:63], v[88:91], v[136:139], v[60:63]
	v_mfma_f32_16x16x32_f16 v[56:59], v[100:103], v[136:139], v[56:59]
	v_mfma_f32_16x16x32_f16 v[44:47], v[88:91], v[148:151], v[44:47]
	v_mfma_f32_16x16x32_f16 v[40:43], v[100:103], v[148:151], v[40:43]
	v_mfma_f32_16x16x32_f16 v[28:31], v[88:91], v[156:159], v[28:31]
	v_mfma_f32_16x16x32_f16 v[24:27], v[100:103], v[156:159], v[24:27]
	v_mfma_f32_16x16x32_f16 v[12:15], v[88:91], v[172:175], v[12:15]
	v_mfma_f32_16x16x32_f16 v[8:11], v[100:103], v[172:175], v[8:11]
	s_barrier
	s_add_u32 s82, s18, 0x80000
	s_addc_u32 s83, s19, 0
	s_add_i32 s81, s76, s24
	v_lshl_add_u64 v[80:81], s[82:83], 0, v[206:207]
	s_mov_b32 m0, s81
	s_nop 0
	global_load_lds_dwordx4 v[80:81], off
	v_lshl_add_u64 v[80:81], s[82:83], 0, v[210:211]
	s_add_i32 m0, s81, 0x2000
	s_nop 0
	global_load_lds_dwordx4 v[80:81], off
	s_waitcnt vmcnt(6)
	s_barrier
	v_mfma_f32_16x16x32_f16 v[52:55], v[176:179], v[132:135], v[52:55]
	v_mfma_f32_16x16x32_f16 v[48:51], v[184:187], v[132:135], v[48:51]
	v_mfma_f32_16x16x32_f16 v[36:39], v[176:179], v[140:143], v[36:39]
	v_mfma_f32_16x16x32_f16 v[32:35], v[184:187], v[140:143], v[32:35]
	v_mfma_f32_16x16x32_f16 v[20:23], v[176:179], v[152:155], v[20:23]
	v_mfma_f32_16x16x32_f16 v[16:19], v[184:187], v[152:155], v[16:19]
	v_mfma_f32_16x16x32_f16 v[4:7], v[176:179], v[160:163], v[4:7]
	v_mfma_f32_16x16x32_f16 v[0:3], v[184:187], v[160:163], v[0:3]
	v_mfma_f32_16x16x32_f16 v[52:55], v[180:183], v[136:139], v[52:55]
	v_mfma_f32_16x16x32_f16 v[48:51], v[188:191], v[136:139], v[48:51]
	v_mfma_f32_16x16x32_f16 v[36:39], v[180:183], v[148:151], v[36:39]
	v_mfma_f32_16x16x32_f16 v[32:35], v[188:191], v[148:151], v[32:35]
	v_mfma_f32_16x16x32_f16 v[20:23], v[180:183], v[156:159], v[20:23]
	v_mfma_f32_16x16x32_f16 v[16:19], v[188:191], v[156:159], v[16:19]
	v_mfma_f32_16x16x32_f16 v[4:7], v[180:183], v[172:175], v[4:7]
	v_mfma_f32_16x16x32_f16 v[0:3], v[188:191], v[172:175], v[0:3]
	s_add_i32 s81, 0, 0x18000
	v_add_u32_e32 v100, s81, v241
	s_barrier
	ds_read_b128 v[80:83], v100
	ds_read_b128 v[88:91], v100 offset:1024
	ds_read_b128 v[96:99], v100 offset:2048
	ds_read_b128 v[100:103], v100 offset:3072
	s_add_u32 s20, s20, 0x80000
	s_addc_u32 s21, s21, 0
	s_mov_b32 m0, s26
	v_lshl_add_u64 v[140:141], s[20:21], 0, v[204:205]
	ds_read_b128 v[132:135], v244 offset:32768
	ds_read_b128 v[136:139], v244 offset:33792
	ds_read_b128 v[148:151], v244 offset:34816
	ds_read_b128 v[152:155], v244 offset:35840
	ds_read_b128 v[156:159], v244 offset:36864
	ds_read_b128 v[160:163], v244 offset:37888
	ds_read_b128 v[172:175], v244 offset:38912
	ds_read_b128 v[176:179], v244 offset:39936
	global_load_lds_dwordx4 v[140:141], off
	v_lshl_add_u64 v[140:141], s[20:21], 0, v[208:209]
	s_mov_b32 m0, s27
	s_nop 0
	global_load_lds_dwordx4 v[140:141], off
	s_waitcnt lgkmcnt(8)
	s_barrier
	s_waitcnt lgkmcnt(0)
	s_waitcnt lgkmcnt(0)
	v_mfma_f32_16x16x32_f16 v[140:143], v[80:83], v[132:135], v[168:171]
	v_mfma_f32_16x16x32_f16 v[168:171], v[88:91], v[136:139], v[140:143]
	v_mfma_f32_16x16x32_f16 v[140:143], v[96:99], v[132:135], v[164:167]
	v_mfma_f32_16x16x32_f16 v[128:131], v[80:83], v[148:151], v[128:131]
	v_mfma_f32_16x16x32_f16 v[124:127], v[96:99], v[148:151], v[124:127]
	v_mfma_f32_16x16x32_f16 v[108:111], v[80:83], v[156:159], v[108:111]
	v_mfma_f32_16x16x32_f16 v[104:107], v[96:99], v[156:159], v[104:107]
	v_mfma_f32_16x16x32_f16 v[76:79], v[80:83], v[172:175], v[76:79]
	v_mfma_f32_16x16x32_f16 v[72:75], v[96:99], v[172:175], v[72:75]
	v_mfma_f32_16x16x32_f16 v[164:167], v[100:103], v[136:139], v[140:143]
	v_mfma_f32_16x16x32_f16 v[128:131], v[88:91], v[152:155], v[128:131]
	v_mfma_f32_16x16x32_f16 v[124:127], v[100:103], v[152:155], v[124:127]
	v_mfma_f32_16x16x32_f16 v[108:111], v[88:91], v[160:163], v[108:111]
	v_mfma_f32_16x16x32_f16 v[104:107], v[100:103], v[160:163], v[104:107]
	v_mfma_f32_16x16x32_f16 v[76:79], v[88:91], v[176:179], v[76:79]
	v_mfma_f32_16x16x32_f16 v[72:75], v[100:103], v[176:179], v[72:75]
	s_barrier
	s_add_i32 s20, 0, 0x1c000
	v_add_u32_e32 v140, s20, v241
	s_add_i32 s21, s81, s24
	ds_read_b128 v[180:183], v140
	ds_read_b128 v[184:187], v140 offset:1024
	ds_read_b128 v[188:191], v140 offset:2048
	ds_read_b128 v[192:195], v140 offset:3072
	v_lshl_add_u64 v[140:141], v[196:197], 0, s[4:5]
	s_mov_b32 m0, s21
	s_nop 0
	global_load_lds_dwordx4 v[140:141], off
	v_lshl_add_u64 v[140:141], v[198:199], 0, s[4:5]
	s_add_i32 m0, s21, 0x2000
	s_nop 0
	global_load_lds_dwordx4 v[140:141], off
	s_barrier
	s_waitcnt lgkmcnt(0)
	s_waitcnt lgkmcnt(0)
	v_mfma_f32_16x16x32_f16 v[140:143], v[180:183], v[132:135], v[144:147]
	v_mfma_f32_16x16x32_f16 v[120:123], v[188:191], v[132:135], v[120:123]
	v_mfma_f32_16x16x32_f16 v[116:119], v[180:183], v[148:151], v[116:119]
	v_mfma_f32_16x16x32_f16 v[112:115], v[188:191], v[148:151], v[112:115]
	v_mfma_f32_16x16x32_f16 v[92:95], v[180:183], v[156:159], v[92:95]
	v_mfma_f32_16x16x32_f16 v[84:87], v[188:191], v[156:159], v[84:87]
	v_mfma_f32_16x16x32_f16 v[68:71], v[180:183], v[172:175], v[68:71]
	v_mfma_f32_16x16x32_f16 v[64:67], v[188:191], v[172:175], v[64:67]
	v_mfma_f32_16x16x32_f16 v[144:147], v[184:187], v[136:139], v[140:143]
	v_mfma_f32_16x16x32_f16 v[140:143], v[192:195], v[136:139], v[120:123]
	v_mfma_f32_16x16x32_f16 v[116:119], v[184:187], v[152:155], v[116:119]
	v_mfma_f32_16x16x32_f16 v[112:115], v[192:195], v[152:155], v[112:115]
	v_mfma_f32_16x16x32_f16 v[92:95], v[184:187], v[160:163], v[92:95]
	v_mfma_f32_16x16x32_f16 v[84:87], v[192:195], v[160:163], v[84:87]
	v_mfma_f32_16x16x32_f16 v[68:71], v[184:187], v[176:179], v[68:71]
	v_mfma_f32_16x16x32_f16 v[64:67], v[192:195], v[176:179], v[64:67]
	s_mov_b32 m0, s35
	v_lshl_add_u64 v[176:177], v[200:201], 0, s[4:5]
	s_barrier
	ds_read_b128 v[120:123], v244 offset:49152
	ds_read_b128 v[132:135], v244 offset:50176
	ds_read_b128 v[136:139], v244 offset:51200
	ds_read_b128 v[148:151], v244 offset:52224
	ds_read_b128 v[152:155], v244 offset:53248
	ds_read_b128 v[156:159], v244 offset:54272
	ds_read_b128 v[160:163], v244 offset:55296
	ds_read_b128 v[172:175], v244 offset:56320
	global_load_lds_dwordx4 v[176:177], off
	v_lshl_add_u64 v[176:177], v[202:203], 0, s[4:5]
	s_mov_b32 m0, s68
	s_nop 0
	global_load_lds_dwordx4 v[176:177], off
	s_barrier
	s_waitcnt lgkmcnt(0)
	s_waitcnt lgkmcnt(0)
	v_mfma_f32_16x16x32_f16 v[60:63], v[80:83], v[120:123], v[60:63]
	v_mfma_f32_16x16x32_f16 v[56:59], v[96:99], v[120:123], v[56:59]
	v_mfma_f32_16x16x32_f16 v[44:47], v[80:83], v[136:139], v[44:47]
	v_mfma_f32_16x16x32_f16 v[40:43], v[96:99], v[136:139], v[40:43]
	v_mfma_f32_16x16x32_f16 v[28:31], v[80:83], v[152:155], v[28:31]
	v_mfma_f32_16x16x32_f16 v[24:27], v[96:99], v[152:155], v[24:27]
	v_mfma_f32_16x16x32_f16 v[12:15], v[80:83], v[160:163], v[12:15]
	v_mfma_f32_16x16x32_f16 v[8:11], v[96:99], v[160:163], v[8:11]
	v_mfma_f32_16x16x32_f16 v[60:63], v[88:91], v[132:135], v[60:63]
	v_mfma_f32_16x16x32_f16 v[56:59], v[100:103], v[132:135], v[56:59]
	v_mfma_f32_16x16x32_f16 v[44:47], v[88:91], v[148:151], v[44:47]
	v_mfma_f32_16x16x32_f16 v[40:43], v[100:103], v[148:151], v[40:43]
	v_mfma_f32_16x16x32_f16 v[28:31], v[88:91], v[156:159], v[28:31]
	v_mfma_f32_16x16x32_f16 v[24:27], v[100:103], v[156:159], v[24:27]
	v_mfma_f32_16x16x32_f16 v[12:15], v[88:91], v[172:175], v[12:15]
	v_mfma_f32_16x16x32_f16 v[8:11], v[100:103], v[172:175], v[8:11]
	s_barrier
	s_add_u32 s18, s18, 0x80080
	s_addc_u32 s19, s19, 0
	s_add_i32 s20, s20, s24
	v_lshl_add_u64 v[80:81], s[18:19], 0, v[206:207]
	s_mov_b32 m0, s20
	s_nop 0
	global_load_lds_dwordx4 v[80:81], off
	v_lshl_add_u64 v[80:81], s[18:19], 0, v[210:211]
	s_add_i32 m0, s20, 0x2000
	s_nop 0
	global_load_lds_dwordx4 v[80:81], off
	s_waitcnt vmcnt(6)
	s_barrier
	v_mfma_f32_16x16x32_f16 v[52:55], v[180:183], v[120:123], v[52:55]
	v_mfma_f32_16x16x32_f16 v[48:51], v[188:191], v[120:123], v[48:51]
	v_mfma_f32_16x16x32_f16 v[36:39], v[180:183], v[136:139], v[36:39]
	v_mfma_f32_16x16x32_f16 v[32:35], v[188:191], v[136:139], v[32:35]
	v_mfma_f32_16x16x32_f16 v[20:23], v[180:183], v[152:155], v[20:23]
	v_mfma_f32_16x16x32_f16 v[16:19], v[188:191], v[152:155], v[16:19]
	v_mfma_f32_16x16x32_f16 v[4:7], v[180:183], v[160:163], v[4:7]
	v_mfma_f32_16x16x32_f16 v[0:3], v[188:191], v[160:163], v[0:3]
	v_mfma_f32_16x16x32_f16 v[52:55], v[184:187], v[132:135], v[52:55]
	v_mfma_f32_16x16x32_f16 v[48:51], v[192:195], v[132:135], v[48:51]
	v_mfma_f32_16x16x32_f16 v[36:39], v[184:187], v[148:151], v[36:39]
	v_mfma_f32_16x16x32_f16 v[32:35], v[192:195], v[148:151], v[32:35]
	v_mfma_f32_16x16x32_f16 v[20:23], v[184:187], v[156:159], v[20:23]
	v_mfma_f32_16x16x32_f16 v[16:19], v[192:195], v[156:159], v[16:19]
	v_mfma_f32_16x16x32_f16 v[4:7], v[184:187], v[172:175], v[4:7]
	v_mfma_f32_16x16x32_f16 v[0:3], v[192:195], v[172:175], v[0:3]
	s_add_i32 s80, s80, 2
	s_add_u32 s16, s16, 0x100
	s_addc_u32 s17, s17, 0
	s_add_u32 s78, s78, 0x100
	s_addc_u32 s79, s79, 0
	s_cmp_gt_u32 s80, 29
	s_barrier
	s_cbranch_scc0 .LBB0_647
	s_setprio 0
	s_lshl_b32 s7, s14, 8
	s_add_i32 s9, s7, 0xffffe000
	s_lshr_b32 s9, s9, 11
	s_mulk_i32 s9, 0x1800
	s_addk_i32 s9, 0x1800
	s_cmp_gt_i32 s14, 31
	s_cselect_b32 s16, s9, 0
	s_ashr_i32 s17, s16, 31
	v_lshl_or_b32 v120, s30, 8, v242
	s_lshl_b64 s[16:17], s[16:17], 2
	s_add_u32 s16, s29, s16
	v_ashrrev_i32_e32 v121, 31, v120
	v_add_u32_e32 v122, s7, v240
	s_addc_u32 s17, s34, s17
	v_lshlrev_b64 v[220:221], 1, v[120:121]
	v_ashrrev_i32_e32 v123, 31, v122
	v_lshl_add_u64 v[88:89], v[120:121], 2, s[16:17]
	v_lshl_add_u64 v[120:121], s[40:41], 0, v[220:221]
	v_lshlrev_b64 v[236:237], 12, v[122:123]
	v_lshl_add_u64 v[132:133], v[120:121], 0, v[236:237]
	global_load_dwordx4 v[96:99], v[88:89], off offset:16
	global_load_dwordx4 v[100:103], v[88:89], off
	global_load_dwordx4 v[80:83], v[88:89], off offset:528
	s_nop 0
	global_load_dwordx4 v[88:91], v[88:89], off offset:512
	s_nop 0
	global_load_dwordx4 v[246:249], v[132:133], off nt
	global_load_dwordx4 v[200:203], v[132:133], off offset:256 nt
	v_or_b32_e32 v132, 16, v122
	v_ashrrev_i32_e32 v133, 31, v132
	v_lshlrev_b64 v[234:235], 12, v[132:133]
	v_lshl_add_u64 v[132:133], v[120:121], 0, v[234:235]
	global_load_dwordx4 v[196:199], v[132:133], off nt
	global_load_dwordx4 v[192:195], v[132:133], off offset:256 nt
	v_or_b32_e32 v132, 32, v122
	v_ashrrev_i32_e32 v133, 31, v132
	v_lshlrev_b64 v[232:233], 12, v[132:133]
	v_lshl_add_u64 v[132:133], v[120:121], 0, v[232:233]
	global_load_dwordx4 v[188:191], v[132:133], off nt
	global_load_dwordx4 v[184:187], v[132:133], off offset:256 nt
	v_or_b32_e32 v122, 48, v122
	v_ashrrev_i32_e32 v123, 31, v122
	v_lshlrev_b64 v[230:231], 12, v[122:123]
	v_lshl_add_u64 v[122:123], v[120:121], 0, v[230:231]
	global_load_dwordx4 v[180:183], v[122:123], off nt
	global_load_dwordx4 v[176:179], v[122:123], off offset:256 nt
	s_mov_b64 s[16:17], 0x80000
	v_lshl_add_u64 v[228:229], v[236:237], 0, s[16:17]
	v_lshl_add_u64 v[122:123], v[120:121], 0, v[228:229]
	global_load_dwordx4 v[172:175], v[122:123], off nt
	global_load_dwordx4 v[160:163], v[122:123], off offset:256 nt
	s_mov_b64 s[16:17], 0x90000
	v_lshl_add_u64 v[226:227], v[236:237], 0, s[16:17]
	v_lshl_add_u64 v[122:123], v[120:121], 0, v[226:227]
	global_load_dwordx4 v[156:159], v[122:123], off nt
	global_load_dwordx4 v[152:155], v[122:123], off offset:256 nt
	s_mov_b64 s[16:17], 0xa0000
	v_lshl_add_u64 v[224:225], v[236:237], 0, s[16:17]
	v_lshl_add_u64 v[122:123], v[120:121], 0, v[224:225]
	global_load_dwordx4 v[148:151], v[122:123], off nt
	global_load_dwordx4 v[136:139], v[122:123], off offset:256 nt
	s_mov_b64 s[16:17], 0xb0000
	v_lshl_add_u64 v[222:223], v[236:237], 0, s[16:17]
	v_lshl_add_u64 v[120:121], v[120:121], 0, v[222:223]
	global_load_dwordx4 v[132:135], v[120:121], off nt
	s_nop 0
	global_load_dwordx4 v[120:123], v[120:121], off offset:256 nt
	s_and_b64 vcc, exec, s[2:3]
	s_mov_b32 s30, s6
	s_mov_b32 s14, s8
	s_mov_b64 s[18:19], s[12:13]
	s_mov_b64 s[16:17], s[10:11]
	s_waitcnt vmcnt(0)
	v_cvt_f32_f16_e32 v250, v246
	v_cvt_f32_f16_sdwa v251, v246 dst_sel:DWORD dst_unused:UNUSED_PAD src0_sel:WORD_1
	v_pk_fma_f32 v[168:169], v[168:169], v[100:101], v[250:251]
	s_nop 0
	v_cvt_pk_f16_f32 v246, v168, v169
	v_cvt_f32_f16_e32 v168, v248
	v_cvt_f32_f16_sdwa v169, v248 dst_sel:DWORD dst_unused:UNUSED_PAD src0_sel:WORD_1
	v_pk_fma_f32 v[164:165], v[164:165], v[96:97], v[168:169]
	s_nop 0
	v_cvt_pk_f16_f32 v248, v164, v165
	v_cvt_f32_f16_e32 v164, v247
	v_cvt_f32_f16_sdwa v165, v247 dst_sel:DWORD dst_unused:UNUSED_PAD src0_sel:WORD_1
	v_pk_fma_f32 v[164:165], v[170:171], v[102:103], v[164:165]
	s_nop 0
	v_cvt_pk_f16_f32 v247, v164, v165
	v_cvt_f32_f16_e32 v164, v249
	v_cvt_f32_f16_sdwa v165, v249 dst_sel:DWORD dst_unused:UNUSED_PAD src0_sel:WORD_1
	v_pk_fma_f32 v[164:165], v[166:167], v[98:99], v[164:165]
	s_nop 0
	v_cvt_pk_f16_f32 v249, v164, v165
	v_lshl_add_u64 v[164:165], s[0:1], 0, v[236:237]
	v_lshl_add_u64 v[168:169], v[164:165], 0, v[220:221]
	v_cvt_f32_f16_e32 v164, v200
	v_cvt_f32_f16_sdwa v165, v200 dst_sel:DWORD dst_unused:UNUSED_PAD src0_sel:WORD_1
	global_store_dwordx4 v[168:169], v[246:249], off
	v_pk_fma_f32 v[144:145], v[144:145], v[88:89], v[164:165]
	s_nop 0
	v_cvt_pk_f16_f32 v164, v144, v145
	v_cvt_f32_f16_e32 v144, v202
	v_cvt_f32_f16_sdwa v145, v202 dst_sel:DWORD dst_unused:UNUSED_PAD src0_sel:WORD_1
	v_pk_fma_f32 v[140:141], v[140:141], v[80:81], v[144:145]
	s_nop 0
	v_cvt_pk_f16_f32 v166, v140, v141
	v_cvt_f32_f16_e32 v140, v201
	v_cvt_f32_f16_sdwa v141, v201 dst_sel:DWORD dst_unused:UNUSED_PAD src0_sel:WORD_1
	v_pk_fma_f32 v[140:141], v[146:147], v[90:91], v[140:141]
	s_nop 0
	v_cvt_pk_f16_f32 v165, v140, v141
	v_cvt_f32_f16_e32 v140, v203
	v_cvt_f32_f16_sdwa v141, v203 dst_sel:DWORD dst_unused:UNUSED_PAD src0_sel:WORD_1
	v_pk_fma_f32 v[140:141], v[142:143], v[82:83], v[140:141]
	s_nop 0
	v_cvt_pk_f16_f32 v167, v140, v141
	v_cvt_f32_f16_e32 v140, v196
	v_cvt_f32_f16_sdwa v141, v196 dst_sel:DWORD dst_unused:UNUSED_PAD src0_sel:WORD_1
	global_store_dwordx4 v[168:169], v[164:167], off offset:256
	v_pk_fma_f32 v[128:129], v[128:129], v[100:101], v[140:141]
	s_nop 0
	v_cvt_pk_f16_f32 v140, v128, v129
	v_cvt_f32_f16_e32 v128, v198
	v_cvt_f32_f16_sdwa v129, v198 dst_sel:DWORD dst_unused:UNUSED_PAD src0_sel:WORD_1
	v_pk_fma_f32 v[124:125], v[124:125], v[96:97], v[128:129]
	s_nop 0
	v_cvt_pk_f16_f32 v142, v124, v125
	v_cvt_f32_f16_e32 v124, v197
	v_cvt_f32_f16_sdwa v125, v197 dst_sel:DWORD dst_unused:UNUSED_PAD src0_sel:WORD_1
	v_pk_fma_f32 v[124:125], v[130:131], v[102:103], v[124:125]
	s_nop 0
	v_cvt_pk_f16_f32 v141, v124, v125
	v_cvt_f32_f16_e32 v124, v199
	v_cvt_f32_f16_sdwa v125, v199 dst_sel:DWORD dst_unused:UNUSED_PAD src0_sel:WORD_1
	v_pk_fma_f32 v[124:125], v[126:127], v[98:99], v[124:125]
	s_nop 0
	v_cvt_pk_f16_f32 v143, v124, v125
	v_lshl_add_u64 v[124:125], s[0:1], 0, v[234:235]
	v_lshl_add_u64 v[128:129], v[124:125], 0, v[220:221]
	v_cvt_f32_f16_e32 v124, v192
	v_cvt_f32_f16_sdwa v125, v192 dst_sel:DWORD dst_unused:UNUSED_PAD src0_sel:WORD_1
	global_store_dwordx4 v[128:129], v[140:143], off
	v_pk_fma_f32 v[116:117], v[116:117], v[88:89], v[124:125]
	s_nop 0
	v_cvt_pk_f16_f32 v124, v116, v117
	v_cvt_f32_f16_e32 v116, v194
	v_cvt_f32_f16_sdwa v117, v194 dst_sel:DWORD dst_unused:UNUSED_PAD src0_sel:WORD_1
	v_pk_fma_f32 v[112:113], v[112:113], v[80:81], v[116:117]
	s_nop 0
	v_cvt_pk_f16_f32 v126, v112, v113
	v_cvt_f32_f16_e32 v112, v193
	v_cvt_f32_f16_sdwa v113, v193 dst_sel:DWORD dst_unused:UNUSED_PAD src0_sel:WORD_1
	v_pk_fma_f32 v[112:113], v[118:119], v[90:91], v[112:113]
	s_nop 0
	v_cvt_pk_f16_f32 v125, v112, v113
	v_cvt_f32_f16_e32 v112, v195
	v_cvt_f32_f16_sdwa v113, v195 dst_sel:DWORD dst_unused:UNUSED_PAD src0_sel:WORD_1
	v_pk_fma_f32 v[112:113], v[114:115], v[82:83], v[112:113]
	s_nop 0
	v_cvt_pk_f16_f32 v127, v112, v113
	v_cvt_f32_f16_e32 v112, v188
	v_cvt_f32_f16_sdwa v113, v188 dst_sel:DWORD dst_unused:UNUSED_PAD src0_sel:WORD_1
	global_store_dwordx4 v[128:129], v[124:127], off offset:256
	v_pk_fma_f32 v[108:109], v[108:109], v[100:101], v[112:113]
	s_nop 0
	v_cvt_pk_f16_f32 v112, v108, v109
	v_cvt_f32_f16_e32 v108, v190
	v_cvt_f32_f16_sdwa v109, v190 dst_sel:DWORD dst_unused:UNUSED_PAD src0_sel:WORD_1
	v_pk_fma_f32 v[104:105], v[104:105], v[96:97], v[108:109]
	s_nop 0
	v_cvt_pk_f16_f32 v114, v104, v105
	v_cvt_f32_f16_e32 v104, v189
	v_cvt_f32_f16_sdwa v105, v189 dst_sel:DWORD dst_unused:UNUSED_PAD src0_sel:WORD_1
	v_pk_fma_f32 v[104:105], v[110:111], v[102:103], v[104:105]
	s_nop 0
	v_cvt_pk_f16_f32 v113, v104, v105
	v_cvt_f32_f16_e32 v104, v191
	v_cvt_f32_f16_sdwa v105, v191 dst_sel:DWORD dst_unused:UNUSED_PAD src0_sel:WORD_1
	v_pk_fma_f32 v[104:105], v[106:107], v[98:99], v[104:105]
	s_nop 0
	v_cvt_pk_f16_f32 v115, v104, v105
	v_lshl_add_u64 v[104:105], s[0:1], 0, v[232:233]
	v_lshl_add_u64 v[108:109], v[104:105], 0, v[220:221]
	v_cvt_f32_f16_e32 v104, v184
	v_cvt_f32_f16_sdwa v105, v184 dst_sel:DWORD dst_unused:UNUSED_PAD src0_sel:WORD_1
	global_store_dwordx4 v[108:109], v[112:115], off
	v_pk_fma_f32 v[92:93], v[92:93], v[88:89], v[104:105]
	s_nop 0
	v_cvt_pk_f16_f32 v104, v92, v93
	v_cvt_f32_f16_e32 v92, v186
	v_cvt_f32_f16_sdwa v93, v186 dst_sel:DWORD dst_unused:UNUSED_PAD src0_sel:WORD_1
	v_pk_fma_f32 v[84:85], v[84:85], v[80:81], v[92:93]
	s_nop 0
	v_cvt_pk_f16_f32 v106, v84, v85
	v_cvt_f32_f16_e32 v84, v185
	v_cvt_f32_f16_sdwa v85, v185 dst_sel:DWORD dst_unused:UNUSED_PAD src0_sel:WORD_1
	v_pk_fma_f32 v[84:85], v[94:95], v[90:91], v[84:85]
	s_nop 0
	v_cvt_pk_f16_f32 v105, v84, v85
	v_cvt_f32_f16_e32 v84, v187
	v_cvt_f32_f16_sdwa v85, v187 dst_sel:DWORD dst_unused:UNUSED_PAD src0_sel:WORD_1
	v_pk_fma_f32 v[84:85], v[86:87], v[82:83], v[84:85]
	s_nop 0
	v_cvt_pk_f16_f32 v107, v84, v85
	v_cvt_f32_f16_e32 v84, v180
	v_cvt_f32_f16_sdwa v85, v180 dst_sel:DWORD dst_unused:UNUSED_PAD src0_sel:WORD_1
	global_store_dwordx4 v[108:109], v[104:107], off offset:256
	v_pk_fma_f32 v[76:77], v[76:77], v[100:101], v[84:85]
	s_nop 0
	v_cvt_pk_f16_f32 v84, v76, v77
	v_cvt_f32_f16_e32 v76, v182
	v_cvt_f32_f16_sdwa v77, v182 dst_sel:DWORD dst_unused:UNUSED_PAD src0_sel:WORD_1
	v_pk_fma_f32 v[72:73], v[72:73], v[96:97], v[76:77]
	s_nop 0
	v_cvt_pk_f16_f32 v86, v72, v73
	v_cvt_f32_f16_e32 v72, v181
	v_cvt_f32_f16_sdwa v73, v181 dst_sel:DWORD dst_unused:UNUSED_PAD src0_sel:WORD_1
	v_pk_fma_f32 v[72:73], v[78:79], v[102:103], v[72:73]
	s_nop 0
	v_cvt_pk_f16_f32 v85, v72, v73
	v_cvt_f32_f16_e32 v72, v183
	v_cvt_f32_f16_sdwa v73, v183 dst_sel:DWORD dst_unused:UNUSED_PAD src0_sel:WORD_1
	v_pk_fma_f32 v[72:73], v[74:75], v[98:99], v[72:73]
	s_nop 0
	v_cvt_pk_f16_f32 v87, v72, v73
	v_lshl_add_u64 v[72:73], s[0:1], 0, v[230:231]
	v_lshl_add_u64 v[76:77], v[72:73], 0, v[220:221]
	v_cvt_f32_f16_e32 v72, v176
	v_cvt_f32_f16_sdwa v73, v176 dst_sel:DWORD dst_unused:UNUSED_PAD src0_sel:WORD_1
	global_store_dwordx4 v[76:77], v[84:87], off
	v_pk_fma_f32 v[68:69], v[68:69], v[88:89], v[72:73]
	s_nop 0
	v_cvt_pk_f16_f32 v72, v68, v69
	v_cvt_f32_f16_e32 v68, v178
	v_cvt_f32_f16_sdwa v69, v178 dst_sel:DWORD dst_unused:UNUSED_PAD src0_sel:WORD_1
	v_pk_fma_f32 v[64:65], v[64:65], v[80:81], v[68:69]
	s_nop 0
	v_cvt_pk_f16_f32 v74, v64, v65
	v_cvt_f32_f16_e32 v64, v177
	v_cvt_f32_f16_sdwa v65, v177 dst_sel:DWORD dst_unused:UNUSED_PAD src0_sel:WORD_1
	v_pk_fma_f32 v[64:65], v[70:71], v[90:91], v[64:65]
	s_nop 0
	v_cvt_pk_f16_f32 v73, v64, v65
	v_cvt_f32_f16_e32 v64, v179
	v_cvt_f32_f16_sdwa v65, v179 dst_sel:DWORD dst_unused:UNUSED_PAD src0_sel:WORD_1
	v_pk_fma_f32 v[64:65], v[66:67], v[82:83], v[64:65]
	s_nop 0
	v_cvt_pk_f16_f32 v75, v64, v65
	v_cvt_f32_f16_e32 v64, v172
	v_cvt_f32_f16_sdwa v65, v172 dst_sel:DWORD dst_unused:UNUSED_PAD src0_sel:WORD_1
	global_store_dwordx4 v[76:77], v[72:75], off offset:256
	v_pk_fma_f32 v[60:61], v[60:61], v[100:101], v[64:65]
	s_nop 0
	v_cvt_pk_f16_f32 v64, v60, v61
	v_cvt_f32_f16_e32 v60, v174
	v_cvt_f32_f16_sdwa v61, v174 dst_sel:DWORD dst_unused:UNUSED_PAD src0_sel:WORD_1
	v_pk_fma_f32 v[56:57], v[56:57], v[96:97], v[60:61]
	s_nop 0
	v_cvt_pk_f16_f32 v66, v56, v57
	v_cvt_f32_f16_e32 v56, v173
	v_cvt_f32_f16_sdwa v57, v173 dst_sel:DWORD dst_unused:UNUSED_PAD src0_sel:WORD_1
	v_pk_fma_f32 v[56:57], v[62:63], v[102:103], v[56:57]
	s_nop 0
	v_cvt_pk_f16_f32 v65, v56, v57
	v_cvt_f32_f16_e32 v56, v175
	v_cvt_f32_f16_sdwa v57, v175 dst_sel:DWORD dst_unused:UNUSED_PAD src0_sel:WORD_1
	v_pk_fma_f32 v[56:57], v[58:59], v[98:99], v[56:57]
	s_nop 0
	v_cvt_pk_f16_f32 v67, v56, v57
	v_lshl_add_u64 v[56:57], s[0:1], 0, v[228:229]
	v_lshl_add_u64 v[60:61], v[56:57], 0, v[220:221]
	v_cvt_f32_f16_e32 v56, v160
	v_cvt_f32_f16_sdwa v57, v160 dst_sel:DWORD dst_unused:UNUSED_PAD src0_sel:WORD_1
	global_store_dwordx4 v[60:61], v[64:67], off
	v_pk_fma_f32 v[52:53], v[52:53], v[88:89], v[56:57]
	s_nop 0
	v_cvt_pk_f16_f32 v56, v52, v53
	v_cvt_f32_f16_e32 v52, v162
	v_cvt_f32_f16_sdwa v53, v162 dst_sel:DWORD dst_unused:UNUSED_PAD src0_sel:WORD_1
	v_pk_fma_f32 v[48:49], v[48:49], v[80:81], v[52:53]
	s_nop 0
	v_cvt_pk_f16_f32 v58, v48, v49
	v_cvt_f32_f16_e32 v48, v161
	v_cvt_f32_f16_sdwa v49, v161 dst_sel:DWORD dst_unused:UNUSED_PAD src0_sel:WORD_1
	v_pk_fma_f32 v[48:49], v[54:55], v[90:91], v[48:49]
	s_nop 0
	v_cvt_pk_f16_f32 v57, v48, v49
	v_cvt_f32_f16_e32 v48, v163
	v_cvt_f32_f16_sdwa v49, v163 dst_sel:DWORD dst_unused:UNUSED_PAD src0_sel:WORD_1
	v_pk_fma_f32 v[48:49], v[50:51], v[82:83], v[48:49]
	s_nop 0
	v_cvt_pk_f16_f32 v59, v48, v49
	v_cvt_f32_f16_e32 v48, v156
	v_cvt_f32_f16_sdwa v49, v156 dst_sel:DWORD dst_unused:UNUSED_PAD src0_sel:WORD_1
	global_store_dwordx4 v[60:61], v[56:59], off offset:256
	v_pk_fma_f32 v[44:45], v[44:45], v[100:101], v[48:49]
	s_nop 0
	v_cvt_pk_f16_f32 v48, v44, v45
	v_cvt_f32_f16_e32 v44, v158
	v_cvt_f32_f16_sdwa v45, v158 dst_sel:DWORD dst_unused:UNUSED_PAD src0_sel:WORD_1
	v_pk_fma_f32 v[40:41], v[40:41], v[96:97], v[44:45]
	s_nop 0
	v_cvt_pk_f16_f32 v50, v40, v41
	v_cvt_f32_f16_e32 v40, v157
	v_cvt_f32_f16_sdwa v41, v157 dst_sel:DWORD dst_unused:UNUSED_PAD src0_sel:WORD_1
	v_pk_fma_f32 v[40:41], v[46:47], v[102:103], v[40:41]
	s_nop 0
	v_cvt_pk_f16_f32 v49, v40, v41
	v_cvt_f32_f16_e32 v40, v159
	v_cvt_f32_f16_sdwa v41, v159 dst_sel:DWORD dst_unused:UNUSED_PAD src0_sel:WORD_1
	v_pk_fma_f32 v[40:41], v[42:43], v[98:99], v[40:41]
	s_nop 0
	v_cvt_pk_f16_f32 v51, v40, v41
	v_lshl_add_u64 v[40:41], s[0:1], 0, v[226:227]
	v_lshl_add_u64 v[44:45], v[40:41], 0, v[220:221]
	v_cvt_f32_f16_e32 v40, v152
	v_cvt_f32_f16_sdwa v41, v152 dst_sel:DWORD dst_unused:UNUSED_PAD src0_sel:WORD_1
	global_store_dwordx4 v[44:45], v[48:51], off
	v_pk_fma_f32 v[36:37], v[36:37], v[88:89], v[40:41]
	s_nop 0
	v_cvt_pk_f16_f32 v40, v36, v37
	v_cvt_f32_f16_e32 v36, v154
	v_cvt_f32_f16_sdwa v37, v154 dst_sel:DWORD dst_unused:UNUSED_PAD src0_sel:WORD_1
	v_pk_fma_f32 v[32:33], v[32:33], v[80:81], v[36:37]
	s_nop 0
	v_cvt_pk_f16_f32 v42, v32, v33
	v_cvt_f32_f16_e32 v32, v153
	v_cvt_f32_f16_sdwa v33, v153 dst_sel:DWORD dst_unused:UNUSED_PAD src0_sel:WORD_1
	v_pk_fma_f32 v[32:33], v[38:39], v[90:91], v[32:33]
	s_nop 0
	v_cvt_pk_f16_f32 v41, v32, v33
	v_cvt_f32_f16_e32 v32, v155
	v_cvt_f32_f16_sdwa v33, v155 dst_sel:DWORD dst_unused:UNUSED_PAD src0_sel:WORD_1
	v_pk_fma_f32 v[32:33], v[34:35], v[82:83], v[32:33]
	s_nop 0
	v_cvt_pk_f16_f32 v43, v32, v33
	v_cvt_f32_f16_e32 v32, v148
	v_cvt_f32_f16_sdwa v33, v148 dst_sel:DWORD dst_unused:UNUSED_PAD src0_sel:WORD_1
	global_store_dwordx4 v[44:45], v[40:43], off offset:256
	v_pk_fma_f32 v[28:29], v[28:29], v[100:101], v[32:33]
	s_nop 0
	v_cvt_pk_f16_f32 v32, v28, v29
	v_cvt_f32_f16_e32 v28, v150
	v_cvt_f32_f16_sdwa v29, v150 dst_sel:DWORD dst_unused:UNUSED_PAD src0_sel:WORD_1
	v_pk_fma_f32 v[24:25], v[24:25], v[96:97], v[28:29]
	s_nop 0
	v_cvt_pk_f16_f32 v34, v24, v25
	v_cvt_f32_f16_e32 v24, v149
	v_cvt_f32_f16_sdwa v25, v149 dst_sel:DWORD dst_unused:UNUSED_PAD src0_sel:WORD_1
	v_pk_fma_f32 v[24:25], v[30:31], v[102:103], v[24:25]
	s_nop 0
	v_cvt_pk_f16_f32 v33, v24, v25
	v_cvt_f32_f16_e32 v24, v151
	v_cvt_f32_f16_sdwa v25, v151 dst_sel:DWORD dst_unused:UNUSED_PAD src0_sel:WORD_1
	v_pk_fma_f32 v[24:25], v[26:27], v[98:99], v[24:25]
	s_nop 0
	v_cvt_pk_f16_f32 v35, v24, v25
	v_lshl_add_u64 v[24:25], s[0:1], 0, v[224:225]
	v_lshl_add_u64 v[28:29], v[24:25], 0, v[220:221]
	v_cvt_f32_f16_e32 v24, v136
	v_cvt_f32_f16_sdwa v25, v136 dst_sel:DWORD dst_unused:UNUSED_PAD src0_sel:WORD_1
	global_store_dwordx4 v[28:29], v[32:35], off
	v_pk_fma_f32 v[20:21], v[20:21], v[88:89], v[24:25]
	s_nop 0
	v_cvt_pk_f16_f32 v24, v20, v21
	v_cvt_f32_f16_e32 v20, v138
	v_cvt_f32_f16_sdwa v21, v138 dst_sel:DWORD dst_unused:UNUSED_PAD src0_sel:WORD_1
	v_pk_fma_f32 v[16:17], v[16:17], v[80:81], v[20:21]
	s_nop 0
	v_cvt_pk_f16_f32 v26, v16, v17
	v_cvt_f32_f16_e32 v16, v137
	v_cvt_f32_f16_sdwa v17, v137 dst_sel:DWORD dst_unused:UNUSED_PAD src0_sel:WORD_1
	v_pk_fma_f32 v[16:17], v[22:23], v[90:91], v[16:17]
	s_nop 0
	v_cvt_pk_f16_f32 v25, v16, v17
	v_cvt_f32_f16_e32 v16, v139
	v_cvt_f32_f16_sdwa v17, v139 dst_sel:DWORD dst_unused:UNUSED_PAD src0_sel:WORD_1
	v_pk_fma_f32 v[16:17], v[18:19], v[82:83], v[16:17]
	s_nop 0
	v_cvt_pk_f16_f32 v27, v16, v17
	v_cvt_f32_f16_e32 v16, v132
	v_cvt_f32_f16_sdwa v17, v132 dst_sel:DWORD dst_unused:UNUSED_PAD src0_sel:WORD_1
	global_store_dwordx4 v[28:29], v[24:27], off offset:256
	v_pk_fma_f32 v[12:13], v[12:13], v[100:101], v[16:17]
	s_nop 0
	v_cvt_pk_f16_f32 v16, v12, v13
	v_cvt_f32_f16_e32 v12, v134
	v_cvt_f32_f16_sdwa v13, v134 dst_sel:DWORD dst_unused:UNUSED_PAD src0_sel:WORD_1
	v_pk_fma_f32 v[8:9], v[8:9], v[96:97], v[12:13]
	s_nop 0
	v_cvt_pk_f16_f32 v18, v8, v9
	v_cvt_f32_f16_e32 v8, v133
	v_cvt_f32_f16_sdwa v9, v133 dst_sel:DWORD dst_unused:UNUSED_PAD src0_sel:WORD_1
	v_pk_fma_f32 v[8:9], v[14:15], v[102:103], v[8:9]
	s_nop 0
	v_cvt_pk_f16_f32 v17, v8, v9
	v_cvt_f32_f16_e32 v8, v135
	v_cvt_f32_f16_sdwa v9, v135 dst_sel:DWORD dst_unused:UNUSED_PAD src0_sel:WORD_1
	v_pk_fma_f32 v[8:9], v[10:11], v[98:99], v[8:9]
	s_nop 0
	v_cvt_pk_f16_f32 v19, v8, v9
	v_lshl_add_u64 v[8:9], s[0:1], 0, v[222:223]
	v_lshl_add_u64 v[12:13], v[8:9], 0, v[220:221]
	v_cvt_f32_f16_e32 v8, v120
	v_cvt_f32_f16_sdwa v9, v120 dst_sel:DWORD dst_unused:UNUSED_PAD src0_sel:WORD_1
	global_store_dwordx4 v[12:13], v[16:19], off
	v_pk_fma_f32 v[4:5], v[4:5], v[88:89], v[8:9]
	s_nop 0
	v_cvt_pk_f16_f32 v8, v4, v5
	v_cvt_f32_f16_e32 v4, v122
	v_cvt_f32_f16_sdwa v5, v122 dst_sel:DWORD dst_unused:UNUSED_PAD src0_sel:WORD_1
	v_pk_fma_f32 v[0:1], v[0:1], v[80:81], v[4:5]
	s_nop 0
	v_cvt_pk_f16_f32 v10, v0, v1
	v_cvt_f32_f16_e32 v0, v121
	v_cvt_f32_f16_sdwa v1, v121 dst_sel:DWORD dst_unused:UNUSED_PAD src0_sel:WORD_1
	v_pk_fma_f32 v[0:1], v[6:7], v[90:91], v[0:1]
	s_nop 0
	v_cvt_pk_f16_f32 v9, v0, v1
	v_cvt_f32_f16_e32 v0, v123
	v_cvt_f32_f16_sdwa v1, v123 dst_sel:DWORD dst_unused:UNUSED_PAD src0_sel:WORD_1
	v_pk_fma_f32 v[0:1], v[2:3], v[82:83], v[0:1]
	s_nop 0
	v_cvt_pk_f16_f32 v11, v0, v1
	global_store_dwordx4 v[12:13], v[8:11], off offset:256
	s_cbranch_vccz .LBB0_640
	s_waitcnt vmcnt(0)
	s_cmpk_gt_u32 s22, 0xff
	s_cbranch_scc1 .LBB0_651
	s_barrier

.LBB0_769:
	s_ashr_i32 s9, s8, 31
	v_cmp_lt_i64_e32 vcc, s[10:11], v[140:141]
	s_lshl_b64 s[10:11], s[8:9], 20
	v_readlane_b32 s52, v254, 21
	v_readlane_b32 s53, v254, 22
	s_add_u32 s10, s52, s10
	s_addc_u32 s11, s53, s11
	s_and_b64 s[12:13], vcc, exec
	s_cselect_b32 s5, s11, s17
	s_cselect_b32 s9, s10, s16
	s_ashr_i32 s7, s6, 31
	s_lshl_b64 s[12:13], s[6:7], 20
	s_add_u32 s12, s48, s12
	s_addc_u32 s13, s49, s13
	s_and_b64 s[20:21], vcc, exec
	s_cselect_b32 s7, s13, s19
	s_cselect_b32 s15, s12, s18
	s_add_u32 s16, s16, 0x80080
	s_addc_u32 s17, s17, 0
	s_add_u32 s76, s18, 0x100
	v_mov_b32_e32 v0, 0
	s_addc_u32 s77, s19, 0
	s_mov_b32 s78, -2
	v_mov_b32_e32 v1, v0
	v_mov_b32_e32 v2, v0
	v_mov_b32_e32 v3, v0
	v_mov_b32_e32 v4, v0
	v_mov_b32_e32 v5, v0
	v_mov_b32_e32 v6, v0
	v_mov_b32_e32 v7, v0
	v_mov_b32_e32 v16, v0
	v_mov_b32_e32 v17, v0
	v_mov_b32_e32 v18, v0
	v_mov_b32_e32 v19, v0
	v_mov_b32_e32 v20, v0
	v_mov_b32_e32 v21, v0
	v_mov_b32_e32 v22, v0
	v_mov_b32_e32 v23, v0
	v_mov_b32_e32 v32, v0
	v_mov_b32_e32 v33, v0
	v_mov_b32_e32 v34, v0
	v_mov_b32_e32 v35, v0
	v_mov_b32_e32 v36, v0
	v_mov_b32_e32 v37, v0
	v_mov_b32_e32 v38, v0
	v_mov_b32_e32 v39, v0
	v_mov_b32_e32 v48, v0
	v_mov_b32_e32 v49, v0
	v_mov_b32_e32 v50, v0
	v_mov_b32_e32 v51, v0
	v_mov_b32_e32 v52, v0
	v_mov_b32_e32 v53, v0
	v_mov_b32_e32 v54, v0
	v_mov_b32_e32 v55, v0
	v_mov_b32_e32 v8, v0
	v_mov_b32_e32 v9, v0
	v_mov_b32_e32 v10, v0
	v_mov_b32_e32 v11, v0
	v_mov_b32_e32 v12, v0
	v_mov_b32_e32 v13, v0
	v_mov_b32_e32 v14, v0
	v_mov_b32_e32 v15, v0
	v_mov_b32_e32 v24, v0
	v_mov_b32_e32 v25, v0
	v_mov_b32_e32 v26, v0
	v_mov_b32_e32 v27, v0
	v_mov_b32_e32 v28, v0
	v_mov_b32_e32 v29, v0
	v_mov_b32_e32 v30, v0
	v_mov_b32_e32 v31, v0
	v_mov_b32_e32 v40, v0
	v_mov_b32_e32 v41, v0
	v_mov_b32_e32 v42, v0
	v_mov_b32_e32 v43, v0
	v_mov_b32_e32 v44, v0
	v_mov_b32_e32 v45, v0
	v_mov_b32_e32 v46, v0
	v_mov_b32_e32 v47, v0
	v_mov_b32_e32 v56, v0
	v_mov_b32_e32 v57, v0
	v_mov_b32_e32 v58, v0
	v_mov_b32_e32 v59, v0
	v_mov_b32_e32 v60, v0
	v_mov_b32_e32 v61, v0
	v_mov_b32_e32 v62, v0
	v_mov_b32_e32 v63, v0
	v_mov_b32_e32 v64, v0
	v_mov_b32_e32 v65, v0
	v_mov_b32_e32 v66, v0
	v_mov_b32_e32 v67, v0
	v_mov_b32_e32 v68, v0
	v_mov_b32_e32 v69, v0
	v_mov_b32_e32 v70, v0
	v_mov_b32_e32 v71, v0
	v_mov_b32_e32 v80, v0
	v_mov_b32_e32 v81, v0
	v_mov_b32_e32 v82, v0
	v_mov_b32_e32 v83, v0
	v_mov_b32_e32 v84, v0
	v_mov_b32_e32 v85, v0
	v_mov_b32_e32 v86, v0
	v_mov_b32_e32 v87, v0
	v_mov_b32_e32 v96, v0
	v_mov_b32_e32 v97, v0
	v_mov_b32_e32 v98, v0
	v_mov_b32_e32 v99, v0
	v_mov_b32_e32 v100, v0
	v_mov_b32_e32 v101, v0
	v_mov_b32_e32 v102, v0
	v_mov_b32_e32 v103, v0
	v_mov_b32_e32 v112, v0
	v_mov_b32_e32 v113, v0
	v_mov_b32_e32 v114, v0
	v_mov_b32_e32 v115, v0
	v_mov_b32_e32 v116, v0
	v_mov_b32_e32 v117, v0
	v_mov_b32_e32 v118, v0
	v_mov_b32_e32 v119, v0
	v_mov_b32_e32 v72, v0
	v_mov_b32_e32 v73, v0
	v_mov_b32_e32 v74, v0
	v_mov_b32_e32 v75, v0
	v_mov_b32_e32 v76, v0
	v_mov_b32_e32 v77, v0
	v_mov_b32_e32 v78, v0
	v_mov_b32_e32 v79, v0
	v_mov_b32_e32 v88, v0
	v_mov_b32_e32 v89, v0
	v_mov_b32_e32 v90, v0
	v_mov_b32_e32 v91, v0
	v_mov_b32_e32 v92, v0
	v_mov_b32_e32 v93, v0
	v_mov_b32_e32 v94, v0
	v_mov_b32_e32 v95, v0
	v_mov_b32_e32 v104, v0
	v_mov_b32_e32 v105, v0
	v_mov_b32_e32 v106, v0
	v_mov_b32_e32 v107, v0
	v_mov_b32_e32 v108, v0
	v_mov_b32_e32 v109, v0
	v_mov_b32_e32 v110, v0
	v_mov_b32_e32 v111, v0
	v_mov_b32_e32 v120, v0
	v_mov_b32_e32 v121, v0
	v_mov_b32_e32 v122, v0
	v_mov_b32_e32 v123, v0
	v_mov_b32_e32 v124, v0
	v_mov_b32_e32 v125, v0
	v_mov_b32_e32 v126, v0
	v_mov_b32_e32 v127, v0
	v_readlane_b32 s54, v254, 23
	v_readlane_b32 s55, v254, 24
	v_readlane_b32 s56, v254, 25
	v_readlane_b32 s57, v254, 26
	v_readlane_b32 s58, v254, 27
	v_readlane_b32 s59, v254, 28
	v_readlane_b32 s60, v254, 29
	v_readlane_b32 s61, v254, 30
	v_readlane_b32 s62, v254, 31
	v_readlane_b32 s63, v254, 32
	v_readlane_b32 s64, v254, 33
	v_readlane_b32 s65, v254, 34
	v_readlane_b32 s66, v254, 35
	v_readlane_b32 s67, v254, 36
.LBB0_770:
	ds_read_b128 v[144:147], v151
	ds_read_b128 v[154:157], v151 offset:1024
	ds_read_b128 v[158:161], v151 offset:2048
	ds_read_b128 v[162:165], v151 offset:3072
	s_add_u32 s18, s16, 0xfff80080
	s_addc_u32 s19, s17, -1
	s_cmp_eq_u32 s78, 28
	s_cselect_b32 s21, s5, s19
	s_cselect_b32 s20, s9, s18
	s_cselect_b32 s19, s7, s77
	s_cselect_b32 s18, s15, s76
	v_lshl_add_u64 v[198:199], s[16:17], 0, v[136:137]
	s_add_i32 m0, s24, 0xc000
	ds_read_b128 v[166:169], v152
	ds_read_b128 v[170:173], v152 offset:1024
	ds_read_b128 v[174:177], v152 offset:2048
	ds_read_b128 v[178:181], v152 offset:3072
	ds_read_b128 v[182:185], v152 offset:4096
	ds_read_b128 v[186:189], v152 offset:5120
	ds_read_b128 v[190:193], v152 offset:6144
	ds_read_b128 v[194:197], v152 offset:7168
	global_load_lds_dwordx4 v[198:199], off
	v_lshl_add_u64 v[198:199], s[16:17], 0, v[138:139]
	s_add_i32 m0, s24, 0xe000
	s_nop 0
	global_load_lds_dwordx4 v[198:199], off
	s_waitcnt lgkmcnt(8)
	s_barrier
	s_waitcnt lgkmcnt(0)
	s_waitcnt lgkmcnt(0)
	v_mfma_f32_16x16x32_f16 v[124:127], v[144:147], v[166:169], v[124:127]
	v_mfma_f32_16x16x32_f16 v[120:123], v[158:161], v[166:169], v[120:123]
	v_mfma_f32_16x16x32_f16 v[108:111], v[144:147], v[174:177], v[108:111]
	v_mfma_f32_16x16x32_f16 v[104:107], v[158:161], v[174:177], v[104:107]
	v_mfma_f32_16x16x32_f16 v[92:95], v[144:147], v[182:185], v[92:95]
	v_mfma_f32_16x16x32_f16 v[88:91], v[158:161], v[182:185], v[88:91]
	v_mfma_f32_16x16x32_f16 v[76:79], v[144:147], v[190:193], v[76:79]
	v_mfma_f32_16x16x32_f16 v[72:75], v[158:161], v[190:193], v[72:75]
	v_mfma_f32_16x16x32_f16 v[124:127], v[154:157], v[170:173], v[124:127]
	v_mfma_f32_16x16x32_f16 v[120:123], v[162:165], v[170:173], v[120:123]
	v_mfma_f32_16x16x32_f16 v[108:111], v[154:157], v[178:181], v[108:111]
	v_mfma_f32_16x16x32_f16 v[104:107], v[162:165], v[178:181], v[104:107]
	v_mfma_f32_16x16x32_f16 v[92:95], v[154:157], v[186:189], v[92:95]
	v_mfma_f32_16x16x32_f16 v[88:91], v[162:165], v[186:189], v[88:91]
	v_mfma_f32_16x16x32_f16 v[76:79], v[154:157], v[194:197], v[76:79]
	v_mfma_f32_16x16x32_f16 v[72:75], v[162:165], v[194:197], v[72:75]
	s_barrier
	s_add_i32 s79, s68, s23
	v_lshl_add_u64 v[214:215], s[18:19], 0, v[130:131]
	s_mov_b32 m0, s79
	ds_read_b128 v[198:201], v153
	ds_read_b128 v[202:205], v153 offset:1024
	ds_read_b128 v[206:209], v153 offset:2048
	ds_read_b128 v[210:213], v153 offset:3072
	global_load_lds_dwordx4 v[214:215], off
	v_lshl_add_u64 v[216:217], s[18:19], 0, v[134:135]
	s_add_i32 m0, s79, 0x2000
	s_nop 0
	global_load_lds_dwordx4 v[216:217], off
	s_barrier
	s_waitcnt lgkmcnt(0)
	s_waitcnt lgkmcnt(0)
	v_mfma_f32_16x16x32_f16 v[116:119], v[198:201], v[166:169], v[116:119]
	v_mfma_f32_16x16x32_f16 v[112:115], v[206:209], v[166:169], v[112:115]
	v_mfma_f32_16x16x32_f16 v[100:103], v[198:201], v[174:177], v[100:103]
	v_mfma_f32_16x16x32_f16 v[96:99], v[206:209], v[174:177], v[96:99]
	v_mfma_f32_16x16x32_f16 v[84:87], v[198:201], v[182:185], v[84:87]
	v_mfma_f32_16x16x32_f16 v[80:83], v[206:209], v[182:185], v[80:83]
	v_mfma_f32_16x16x32_f16 v[68:71], v[198:201], v[190:193], v[68:71]
	v_mfma_f32_16x16x32_f16 v[64:67], v[206:209], v[190:193], v[64:67]
	v_mfma_f32_16x16x32_f16 v[116:119], v[202:205], v[170:173], v[116:119]
	v_mfma_f32_16x16x32_f16 v[112:115], v[210:213], v[170:173], v[112:115]
	v_mfma_f32_16x16x32_f16 v[100:103], v[202:205], v[178:181], v[100:103]
	v_mfma_f32_16x16x32_f16 v[96:99], v[210:213], v[178:181], v[96:99]
	v_mfma_f32_16x16x32_f16 v[84:87], v[202:205], v[186:189], v[84:87]
	v_mfma_f32_16x16x32_f16 v[80:83], v[210:213], v[186:189], v[80:83]
	v_mfma_f32_16x16x32_f16 v[68:71], v[202:205], v[194:197], v[68:71]
	v_mfma_f32_16x16x32_f16 v[64:67], v[210:213], v[194:197], v[64:67]
	s_mov_b32 m0, s24
	v_lshl_add_u64 v[218:219], s[20:21], 0, v[128:129]
	s_barrier
	ds_read_b128 v[166:169], v152 offset:16384
	ds_read_b128 v[170:173], v152 offset:17408
	ds_read_b128 v[174:177], v152 offset:18432
	ds_read_b128 v[178:181], v152 offset:19456
	ds_read_b128 v[182:185], v152 offset:20480
	ds_read_b128 v[186:189], v152 offset:21504
	ds_read_b128 v[190:193], v152 offset:22528
	ds_read_b128 v[194:197], v152 offset:23552
	global_load_lds_dwordx4 v[218:219], off
	v_lshl_add_u64 v[220:221], s[20:21], 0, v[132:133]
	s_mov_b32 m0, s25
	s_nop 0
	global_load_lds_dwordx4 v[220:221], off
	s_barrier
	s_waitcnt lgkmcnt(0)
	s_waitcnt lgkmcnt(0)
	v_mfma_f32_16x16x32_f16 v[60:63], v[144:147], v[166:169], v[60:63]
	v_mfma_f32_16x16x32_f16 v[56:59], v[158:161], v[166:169], v[56:59]
	v_mfma_f32_16x16x32_f16 v[44:47], v[144:147], v[174:177], v[44:47]
	v_mfma_f32_16x16x32_f16 v[40:43], v[158:161], v[174:177], v[40:43]
	v_mfma_f32_16x16x32_f16 v[28:31], v[144:147], v[182:185], v[28:31]
	v_mfma_f32_16x16x32_f16 v[24:27], v[158:161], v[182:185], v[24:27]
	v_mfma_f32_16x16x32_f16 v[12:15], v[144:147], v[190:193], v[12:15]
	v_mfma_f32_16x16x32_f16 v[8:11], v[158:161], v[190:193], v[8:11]
	v_mfma_f32_16x16x32_f16 v[60:63], v[154:157], v[170:173], v[60:63]
	v_mfma_f32_16x16x32_f16 v[56:59], v[162:165], v[170:173], v[56:59]
	v_mfma_f32_16x16x32_f16 v[44:47], v[154:157], v[178:181], v[44:47]
	v_mfma_f32_16x16x32_f16 v[40:43], v[162:165], v[178:181], v[40:43]
	v_mfma_f32_16x16x32_f16 v[28:31], v[154:157], v[186:189], v[28:31]
	v_mfma_f32_16x16x32_f16 v[24:27], v[162:165], v[186:189], v[24:27]
	v_mfma_f32_16x16x32_f16 v[12:15], v[154:157], v[194:197], v[12:15]
	v_mfma_f32_16x16x32_f16 v[8:11], v[162:165], v[194:197], v[8:11]
	s_barrier
	s_add_u32 s80, s18, 0x80000
	s_addc_u32 s81, s19, 0
	s_add_i32 s79, s69, s23
	v_lshl_add_u64 v[144:145], s[80:81], 0, v[130:131]
	s_mov_b32 m0, s79
	s_nop 0
	global_load_lds_dwordx4 v[144:145], off
	v_lshl_add_u64 v[144:145], s[80:81], 0, v[134:135]
	s_add_i32 m0, s79, 0x2000
	s_nop 0
	global_load_lds_dwordx4 v[144:145], off
	s_waitcnt vmcnt(6)
	s_barrier
	v_mfma_f32_16x16x32_f16 v[52:55], v[198:201], v[166:169], v[52:55]
	v_mfma_f32_16x16x32_f16 v[48:51], v[206:209], v[166:169], v[48:51]
	v_mfma_f32_16x16x32_f16 v[36:39], v[198:201], v[174:177], v[36:39]
	v_mfma_f32_16x16x32_f16 v[32:35], v[206:209], v[174:177], v[32:35]
	v_mfma_f32_16x16x32_f16 v[20:23], v[198:201], v[182:185], v[20:23]
	v_mfma_f32_16x16x32_f16 v[16:19], v[206:209], v[182:185], v[16:19]
	v_mfma_f32_16x16x32_f16 v[4:7], v[198:201], v[190:193], v[4:7]
	v_mfma_f32_16x16x32_f16 v[0:3], v[206:209], v[190:193], v[0:3]
	v_mfma_f32_16x16x32_f16 v[52:55], v[202:205], v[170:173], v[52:55]
	v_mfma_f32_16x16x32_f16 v[48:51], v[210:213], v[170:173], v[48:51]
	v_mfma_f32_16x16x32_f16 v[36:39], v[202:205], v[178:181], v[36:39]
	v_mfma_f32_16x16x32_f16 v[32:35], v[210:213], v[178:181], v[32:35]
	v_mfma_f32_16x16x32_f16 v[20:23], v[202:205], v[186:189], v[20:23]
	v_mfma_f32_16x16x32_f16 v[16:19], v[210:213], v[186:189], v[16:19]
	v_mfma_f32_16x16x32_f16 v[4:7], v[202:205], v[194:197], v[4:7]
	v_mfma_f32_16x16x32_f16 v[0:3], v[210:213], v[194:197], v[0:3]
	s_add_i32 s79, 0, 0x18000
	v_add_u32_e32 v162, s79, v149
	s_barrier
	ds_read_b128 v[144:147], v162
	ds_read_b128 v[154:157], v162 offset:1024
	ds_read_b128 v[158:161], v162 offset:2048
	ds_read_b128 v[162:165], v162 offset:3072
	s_add_u32 s20, s20, 0x80000
	s_addc_u32 s21, s21, 0
	s_mov_b32 m0, s26
	v_lshl_add_u64 v[198:199], s[20:21], 0, v[128:129]
	ds_read_b128 v[166:169], v152 offset:32768
	ds_read_b128 v[170:173], v152 offset:33792
	ds_read_b128 v[174:177], v152 offset:34816
	ds_read_b128 v[178:181], v152 offset:35840
	ds_read_b128 v[182:185], v152 offset:36864
	ds_read_b128 v[186:189], v152 offset:37888
	ds_read_b128 v[190:193], v152 offset:38912
	ds_read_b128 v[194:197], v152 offset:39936
	global_load_lds_dwordx4 v[198:199], off
	v_lshl_add_u64 v[198:199], s[20:21], 0, v[132:133]
	s_mov_b32 m0, s27
	s_nop 0
	global_load_lds_dwordx4 v[198:199], off
	s_waitcnt lgkmcnt(8)
	s_barrier
	s_waitcnt lgkmcnt(0)
	s_waitcnt lgkmcnt(0)
	v_mfma_f32_16x16x32_f16 v[124:127], v[144:147], v[166:169], v[124:127]
	v_mfma_f32_16x16x32_f16 v[120:123], v[158:161], v[166:169], v[120:123]
	v_mfma_f32_16x16x32_f16 v[108:111], v[144:147], v[174:177], v[108:111]
	v_mfma_f32_16x16x32_f16 v[104:107], v[158:161], v[174:177], v[104:107]
	v_mfma_f32_16x16x32_f16 v[92:95], v[144:147], v[182:185], v[92:95]
	v_mfma_f32_16x16x32_f16 v[88:91], v[158:161], v[182:185], v[88:91]
	v_mfma_f32_16x16x32_f16 v[76:79], v[144:147], v[190:193], v[76:79]
	v_mfma_f32_16x16x32_f16 v[72:75], v[158:161], v[190:193], v[72:75]
	v_mfma_f32_16x16x32_f16 v[124:127], v[154:157], v[170:173], v[124:127]
	v_mfma_f32_16x16x32_f16 v[120:123], v[162:165], v[170:173], v[120:123]
	v_mfma_f32_16x16x32_f16 v[108:111], v[154:157], v[178:181], v[108:111]
	v_mfma_f32_16x16x32_f16 v[104:107], v[162:165], v[178:181], v[104:107]
	v_mfma_f32_16x16x32_f16 v[92:95], v[154:157], v[186:189], v[92:95]
	v_mfma_f32_16x16x32_f16 v[88:91], v[162:165], v[186:189], v[88:91]
	v_mfma_f32_16x16x32_f16 v[76:79], v[154:157], v[194:197], v[76:79]
	v_mfma_f32_16x16x32_f16 v[72:75], v[162:165], v[194:197], v[72:75]
	s_barrier
	s_add_i32 s20, 0, 0x1c000
	s_add_i32 s21, s79, s23
	v_add_u32_e32 v210, s20, v149
	v_lshl_add_u64 v[214:215], v[214:215], 0, s[0:1]
	s_mov_b32 m0, s21
	ds_read_b128 v[198:201], v210
	ds_read_b128 v[202:205], v210 offset:1024
	ds_read_b128 v[206:209], v210 offset:2048
	ds_read_b128 v[210:213], v210 offset:3072
	global_load_lds_dwordx4 v[214:215], off
	v_lshl_add_u64 v[214:215], v[216:217], 0, s[0:1]
	s_add_i32 m0, s21, 0x2000
	s_nop 0
	global_load_lds_dwordx4 v[214:215], off
	s_barrier
	s_waitcnt lgkmcnt(0)
	s_waitcnt lgkmcnt(0)
	v_mfma_f32_16x16x32_f16 v[116:119], v[198:201], v[166:169], v[116:119]
	v_mfma_f32_16x16x32_f16 v[112:115], v[206:209], v[166:169], v[112:115]
	v_mfma_f32_16x16x32_f16 v[100:103], v[198:201], v[174:177], v[100:103]
	v_mfma_f32_16x16x32_f16 v[96:99], v[206:209], v[174:177], v[96:99]
	v_mfma_f32_16x16x32_f16 v[84:87], v[198:201], v[182:185], v[84:87]
	v_mfma_f32_16x16x32_f16 v[80:83], v[206:209], v[182:185], v[80:83]
	v_mfma_f32_16x16x32_f16 v[68:71], v[198:201], v[190:193], v[68:71]
	v_mfma_f32_16x16x32_f16 v[64:67], v[206:209], v[190:193], v[64:67]
	v_mfma_f32_16x16x32_f16 v[116:119], v[202:205], v[170:173], v[116:119]
	v_mfma_f32_16x16x32_f16 v[112:115], v[210:213], v[170:173], v[112:115]
	v_mfma_f32_16x16x32_f16 v[100:103], v[202:205], v[178:181], v[100:103]
	v_mfma_f32_16x16x32_f16 v[96:99], v[210:213], v[178:181], v[96:99]
	v_mfma_f32_16x16x32_f16 v[84:87], v[202:205], v[186:189], v[84:87]
	v_mfma_f32_16x16x32_f16 v[80:83], v[210:213], v[186:189], v[80:83]
	v_mfma_f32_16x16x32_f16 v[68:71], v[202:205], v[194:197], v[68:71]
	v_mfma_f32_16x16x32_f16 v[64:67], v[210:213], v[194:197], v[64:67]
	s_mov_b32 m0, s29
	v_lshl_add_u64 v[214:215], v[218:219], 0, s[0:1]
	s_barrier
	ds_read_b128 v[166:169], v152 offset:49152
	ds_read_b128 v[170:173], v152 offset:50176
	ds_read_b128 v[174:177], v152 offset:51200
	ds_read_b128 v[178:181], v152 offset:52224
	ds_read_b128 v[182:185], v152 offset:53248
	ds_read_b128 v[186:189], v152 offset:54272
	ds_read_b128 v[190:193], v152 offset:55296
	ds_read_b128 v[194:197], v152 offset:56320
	global_load_lds_dwordx4 v[214:215], off
	v_lshl_add_u64 v[214:215], v[220:221], 0, s[0:1]
	s_mov_b32 m0, s30
	s_nop 0
	global_load_lds_dwordx4 v[214:215], off
	s_barrier
	s_waitcnt lgkmcnt(0)
	s_waitcnt lgkmcnt(0)
	v_mfma_f32_16x16x32_f16 v[60:63], v[144:147], v[166:169], v[60:63]
	v_mfma_f32_16x16x32_f16 v[56:59], v[158:161], v[166:169], v[56:59]
	v_mfma_f32_16x16x32_f16 v[44:47], v[144:147], v[174:177], v[44:47]
	v_mfma_f32_16x16x32_f16 v[40:43], v[158:161], v[174:177], v[40:43]
	v_mfma_f32_16x16x32_f16 v[28:31], v[144:147], v[182:185], v[28:31]
	v_mfma_f32_16x16x32_f16 v[24:27], v[158:161], v[182:185], v[24:27]
	v_mfma_f32_16x16x32_f16 v[12:15], v[144:147], v[190:193], v[12:15]
	v_mfma_f32_16x16x32_f16 v[8:11], v[158:161], v[190:193], v[8:11]
	v_mfma_f32_16x16x32_f16 v[60:63], v[154:157], v[170:173], v[60:63]
	v_mfma_f32_16x16x32_f16 v[56:59], v[162:165], v[170:173], v[56:59]
	v_mfma_f32_16x16x32_f16 v[44:47], v[154:157], v[178:181], v[44:47]
	v_mfma_f32_16x16x32_f16 v[40:43], v[162:165], v[178:181], v[40:43]
	v_mfma_f32_16x16x32_f16 v[28:31], v[154:157], v[186:189], v[28:31]
	v_mfma_f32_16x16x32_f16 v[24:27], v[162:165], v[186:189], v[24:27]
	v_mfma_f32_16x16x32_f16 v[12:15], v[154:157], v[194:197], v[12:15]
	v_mfma_f32_16x16x32_f16 v[8:11], v[162:165], v[194:197], v[8:11]
	s_barrier
	s_add_u32 s18, s18, 0x80080
	s_addc_u32 s19, s19, 0
	s_add_i32 s20, s20, s23
	v_lshl_add_u64 v[144:145], s[18:19], 0, v[130:131]
	s_mov_b32 m0, s20
	s_nop 0
	global_load_lds_dwordx4 v[144:145], off
	v_lshl_add_u64 v[144:145], s[18:19], 0, v[134:135]
	s_add_i32 m0, s20, 0x2000
	s_nop 0
	global_load_lds_dwordx4 v[144:145], off
	s_waitcnt vmcnt(6)
	s_barrier
	v_mfma_f32_16x16x32_f16 v[52:55], v[198:201], v[166:169], v[52:55]
	v_mfma_f32_16x16x32_f16 v[48:51], v[206:209], v[166:169], v[48:51]
	v_mfma_f32_16x16x32_f16 v[36:39], v[198:201], v[174:177], v[36:39]
	v_mfma_f32_16x16x32_f16 v[32:35], v[206:209], v[174:177], v[32:35]
	v_mfma_f32_16x16x32_f16 v[20:23], v[198:201], v[182:185], v[20:23]
	v_mfma_f32_16x16x32_f16 v[16:19], v[206:209], v[182:185], v[16:19]
	v_mfma_f32_16x16x32_f16 v[4:7], v[198:201], v[190:193], v[4:7]
	v_mfma_f32_16x16x32_f16 v[0:3], v[206:209], v[190:193], v[0:3]
	v_mfma_f32_16x16x32_f16 v[52:55], v[202:205], v[170:173], v[52:55]
	v_mfma_f32_16x16x32_f16 v[48:51], v[210:213], v[170:173], v[48:51]
	v_mfma_f32_16x16x32_f16 v[36:39], v[202:205], v[178:181], v[36:39]
	v_mfma_f32_16x16x32_f16 v[32:35], v[210:213], v[178:181], v[32:35]
	v_mfma_f32_16x16x32_f16 v[20:23], v[202:205], v[186:189], v[20:23]
	v_mfma_f32_16x16x32_f16 v[16:19], v[210:213], v[186:189], v[16:19]
	v_mfma_f32_16x16x32_f16 v[4:7], v[202:205], v[194:197], v[4:7]
	v_mfma_f32_16x16x32_f16 v[0:3], v[210:213], v[194:197], v[0:3]
	s_add_i32 s78, s78, 2
	s_add_u32 s16, s16, 0x100
	s_addc_u32 s17, s17, 0
	s_add_u32 s76, s76, 0x100
	s_addc_u32 s77, s77, 0
	s_cmp_gt_u32 s78, 29
	s_barrier
	s_cbranch_scc0 .LBB0_770
	s_setprio 0
	v_readlane_b32 s52, v254, 21
	v_readlane_b32 s54, v254, 23
	v_readlane_b32 s55, v254, 24
	v_lshl_add_u32 v154, s14, 8, v148
	v_lshl_or_b32 v144, s4, 8, v150
	v_mov_b64_e32 v[146:147], s[54:55]
	v_mad_i64_i32 v[146:147], s[4:5], v154, s70, v[146:147]
	v_cmp_gt_i32_e32 vcc, s71, v144
	v_ashrrev_i32_e32 v145, 31, v144
	v_readlane_b32 s53, v254, 22
	v_readlane_b32 s56, v254, 25
	v_readlane_b32 s57, v254, 26
	v_readlane_b32 s58, v254, 27
	v_readlane_b32 s59, v254, 28
	v_readlane_b32 s60, v254, 29
	v_readlane_b32 s61, v254, 30
	v_readlane_b32 s62, v254, 31
	v_readlane_b32 s63, v254, 32
	v_readlane_b32 s64, v254, 33
	v_readlane_b32 s65, v254, 34
	v_readlane_b32 s66, v254, 35
	v_readlane_b32 s67, v254, 36
	s_and_saveexec_b64 s[4:5], vcc
	s_cbranch_execz .LBB0_773
	v_cvt_pk_f16_f32 v123, v122, v123
	v_cvt_pk_f16_f32 v122, v120, v121
	v_cvt_pk_f16_f32 v121, v126, v127
	v_cvt_pk_f16_f32 v120, v124, v125
	v_lshl_add_u64 v[124:125], v[144:145], 1, v[146:147]
	global_store_dwordx4 v[124:125], v[120:123], off

.LBB0_1184:
	v_readlane_b32 s64, v254, 21
	s_ashr_i32 s17, s16, 31
	v_readlane_b32 s65, v254, 22
	v_cmp_lt_i64_e32 vcc, s[18:19], v[216:217]
	s_lshl_b64 s[18:19], s[16:17], 20
	s_mov_b64 s[52:53], s[64:65]
	s_add_u32 s18, s52, s18
	s_addc_u32 s19, s53, s19
	s_and_b64 s[20:21], vcc, exec
	s_cselect_b32 s17, s19, s25
	s_cselect_b32 s31, s18, s24
	s_ashr_i32 s15, s14, 31
	s_lshl_b64 s[20:21], s[14:15], 20
	s_add_u32 s20, s36, s20
	s_addc_u32 s21, s37, s21
	s_and_b64 s[28:29], vcc, exec
	s_cselect_b32 s15, s21, s27
	s_cselect_b32 s61, s20, s26
	s_add_u32 s24, s24, 0x80080
	s_addc_u32 s25, s25, 0
	s_add_u32 s62, s26, 0x100
	v_mov_b32_e32 v0, 0
	s_addc_u32 s63, s27, 0
	s_mov_b32 s64, -2
	v_mov_b32_e32 v1, v0
	v_mov_b32_e32 v2, v0
	v_mov_b32_e32 v3, v0
	v_mov_b32_e32 v4, v0
	v_mov_b32_e32 v5, v0
	v_mov_b32_e32 v6, v0
	v_mov_b32_e32 v7, v0
	v_mov_b32_e32 v16, v0
	v_mov_b32_e32 v17, v0
	v_mov_b32_e32 v18, v0
	v_mov_b32_e32 v19, v0
	v_mov_b32_e32 v20, v0
	v_mov_b32_e32 v21, v0
	v_mov_b32_e32 v22, v0
	v_mov_b32_e32 v23, v0
	v_mov_b32_e32 v32, v0
	v_mov_b32_e32 v33, v0
	v_mov_b32_e32 v34, v0
	v_mov_b32_e32 v35, v0
	v_mov_b32_e32 v36, v0
	v_mov_b32_e32 v37, v0
	v_mov_b32_e32 v38, v0
	v_mov_b32_e32 v39, v0
	v_mov_b32_e32 v48, v0
	v_mov_b32_e32 v49, v0
	v_mov_b32_e32 v50, v0
	v_mov_b32_e32 v51, v0
	v_mov_b32_e32 v52, v0
	v_mov_b32_e32 v53, v0
	v_mov_b32_e32 v54, v0
	v_mov_b32_e32 v55, v0
	v_mov_b32_e32 v8, v0
	v_mov_b32_e32 v9, v0
	v_mov_b32_e32 v10, v0
	v_mov_b32_e32 v11, v0
	v_mov_b32_e32 v12, v0
	v_mov_b32_e32 v13, v0
	v_mov_b32_e32 v14, v0
	v_mov_b32_e32 v15, v0
	v_mov_b32_e32 v24, v0
	v_mov_b32_e32 v25, v0
	v_mov_b32_e32 v26, v0
	v_mov_b32_e32 v27, v0
	v_mov_b32_e32 v28, v0
	v_mov_b32_e32 v29, v0
	v_mov_b32_e32 v30, v0
	v_mov_b32_e32 v31, v0
	v_mov_b32_e32 v40, v0
	v_mov_b32_e32 v41, v0
	v_mov_b32_e32 v42, v0
	v_mov_b32_e32 v43, v0
	v_mov_b32_e32 v44, v0
	v_mov_b32_e32 v45, v0
	v_mov_b32_e32 v46, v0
	v_mov_b32_e32 v47, v0
	v_mov_b32_e32 v56, v0
	v_mov_b32_e32 v57, v0
	v_mov_b32_e32 v58, v0
	v_mov_b32_e32 v59, v0
	v_mov_b32_e32 v60, v0
	v_mov_b32_e32 v61, v0
	v_mov_b32_e32 v62, v0
	v_mov_b32_e32 v63, v0
	v_mov_b32_e32 v64, v0
	v_mov_b32_e32 v65, v0
	v_mov_b32_e32 v66, v0
	v_mov_b32_e32 v67, v0
	v_mov_b32_e32 v68, v0
	v_mov_b32_e32 v69, v0
	v_mov_b32_e32 v70, v0
	v_mov_b32_e32 v71, v0
	v_mov_b32_e32 v80, v0
	v_mov_b32_e32 v81, v0
	v_mov_b32_e32 v82, v0
	v_mov_b32_e32 v83, v0
	v_mov_b32_e32 v84, v0
	v_mov_b32_e32 v85, v0
	v_mov_b32_e32 v86, v0
	v_mov_b32_e32 v87, v0
	v_mov_b32_e32 v104, v0
	v_mov_b32_e32 v105, v0
	v_mov_b32_e32 v106, v0
	v_mov_b32_e32 v107, v0
	v_mov_b32_e32 v112, v0
	v_mov_b32_e32 v113, v0
	v_mov_b32_e32 v114, v0
	v_mov_b32_e32 v115, v0
	v_mov_b32_e32 v132, v0
	v_mov_b32_e32 v133, v0
	v_mov_b32_e32 v134, v0
	v_mov_b32_e32 v135, v0
	v_mov_b32_e32 v140, v0
	v_mov_b32_e32 v141, v0
	v_mov_b32_e32 v142, v0
	v_mov_b32_e32 v143, v0
	v_mov_b32_e32 v72, v0
	v_mov_b32_e32 v73, v0
	v_mov_b32_e32 v74, v0
	v_mov_b32_e32 v75, v0
	v_mov_b32_e32 v76, v0
	v_mov_b32_e32 v77, v0
	v_mov_b32_e32 v78, v0
	v_mov_b32_e32 v79, v0
	v_mov_b32_e32 v92, v0
	v_mov_b32_e32 v93, v0
	v_mov_b32_e32 v94, v0
	v_mov_b32_e32 v95, v0
	v_mov_b32_e32 v100, v0
	v_mov_b32_e32 v101, v0
	v_mov_b32_e32 v102, v0
	v_mov_b32_e32 v103, v0
	v_mov_b32_e32 v120, v0
	v_mov_b32_e32 v121, v0
	v_mov_b32_e32 v122, v0
	v_mov_b32_e32 v123, v0
	v_mov_b32_e32 v124, v0
	v_mov_b32_e32 v125, v0
	v_mov_b32_e32 v126, v0
	v_mov_b32_e32 v127, v0
	v_mov_b32_e32 v156, v0
	v_mov_b32_e32 v157, v0
	v_mov_b32_e32 v158, v0
	v_mov_b32_e32 v159, v0
	v_mov_b32_e32 v160, v0
	v_mov_b32_e32 v161, v0
	v_mov_b32_e32 v162, v0
	v_mov_b32_e32 v163, v0
	v_readlane_b32 s66, v254, 23
	v_readlane_b32 s67, v254, 24
	v_readlane_b32 s68, v254, 25
	v_readlane_b32 s69, v254, 26
	v_readlane_b32 s70, v254, 27
	v_readlane_b32 s71, v254, 28
	v_readlane_b32 s72, v254, 29
	v_readlane_b32 s73, v254, 30
	v_readlane_b32 s74, v254, 31
	v_readlane_b32 s75, v254, 32
	v_readlane_b32 s76, v254, 33
	v_readlane_b32 s77, v254, 34
	v_readlane_b32 s78, v254, 35
	v_readlane_b32 s79, v254, 36
.LBB0_1185:
	ds_read_b128 v[88:91], v243
	ds_read_b128 v[96:99], v243 offset:1024
	ds_read_b128 v[108:111], v243 offset:2048
	ds_read_b128 v[116:119], v243 offset:3072
	s_add_u32 s26, s24, 0xfff80080
	s_addc_u32 s27, s25, -1
	s_cmp_eq_u32 s64, 28
	s_cselect_b32 s29, s17, s27
	s_cselect_b32 s28, s31, s26
	s_cselect_b32 s27, s15, s63
	s_cselect_b32 s26, s61, s62
	v_lshl_add_u64 v[176:177], s[24:25], 0, v[212:213]
	s_add_i32 m0, s23, 0xc000
	ds_read_b128 v[128:131], v244
	ds_read_b128 v[136:139], v244 offset:1024
	ds_read_b128 v[144:147], v244 offset:2048
	ds_read_b128 v[148:151], v244 offset:3072
	ds_read_b128 v[152:155], v244 offset:4096
	ds_read_b128 v[164:167], v244 offset:5120
	ds_read_b128 v[168:171], v244 offset:6144
	ds_read_b128 v[172:175], v244 offset:7168
	global_load_lds_dwordx4 v[176:177], off
	v_lshl_add_u64 v[176:177], s[24:25], 0, v[214:215]
	s_add_i32 m0, s23, 0xe000
	s_nop 0
	global_load_lds_dwordx4 v[176:177], off
	s_waitcnt lgkmcnt(8)
	s_barrier
	s_waitcnt lgkmcnt(0)
	s_waitcnt lgkmcnt(0)
	v_mfma_f32_16x16x32_f16 v[160:163], v[88:91], v[128:131], v[160:163]
	v_mfma_f32_16x16x32_f16 v[156:159], v[108:111], v[128:131], v[156:159]
	v_mfma_f32_16x16x32_f16 v[124:127], v[88:91], v[144:147], v[124:127]
	v_mfma_f32_16x16x32_f16 v[120:123], v[108:111], v[144:147], v[120:123]
	v_mfma_f32_16x16x32_f16 v[100:103], v[88:91], v[152:155], v[100:103]
	v_mfma_f32_16x16x32_f16 v[92:95], v[108:111], v[152:155], v[92:95]
	v_mfma_f32_16x16x32_f16 v[76:79], v[88:91], v[168:171], v[76:79]
	v_mfma_f32_16x16x32_f16 v[72:75], v[108:111], v[168:171], v[72:75]
	v_mfma_f32_16x16x32_f16 v[160:163], v[96:99], v[136:139], v[160:163]
	v_mfma_f32_16x16x32_f16 v[156:159], v[116:119], v[136:139], v[156:159]
	v_mfma_f32_16x16x32_f16 v[124:127], v[96:99], v[148:151], v[124:127]
	v_mfma_f32_16x16x32_f16 v[120:123], v[116:119], v[148:151], v[120:123]
	v_mfma_f32_16x16x32_f16 v[100:103], v[96:99], v[164:167], v[100:103]
	v_mfma_f32_16x16x32_f16 v[92:95], v[116:119], v[164:167], v[92:95]
	v_mfma_f32_16x16x32_f16 v[76:79], v[96:99], v[172:175], v[76:79]
	v_mfma_f32_16x16x32_f16 v[72:75], v[116:119], v[172:175], v[72:75]
	s_barrier
	s_add_i32 s65, s59, s44
	v_lshl_add_u64 v[192:193], s[26:27], 0, v[206:207]
	s_mov_b32 m0, s65
	ds_read_b128 v[176:179], v245
	ds_read_b128 v[180:183], v245 offset:1024
	ds_read_b128 v[184:187], v245 offset:2048
	ds_read_b128 v[188:191], v245 offset:3072
	global_load_lds_dwordx4 v[192:193], off
	v_lshl_add_u64 v[194:195], s[26:27], 0, v[210:211]
	s_add_i32 m0, s65, 0x2000
	s_nop 0
	global_load_lds_dwordx4 v[194:195], off
	s_barrier
	s_waitcnt lgkmcnt(0)
	s_waitcnt lgkmcnt(0)
	v_mfma_f32_16x16x32_f16 v[140:143], v[176:179], v[128:131], v[140:143]
	v_mfma_f32_16x16x32_f16 v[112:115], v[176:179], v[144:147], v[112:115]
	v_mfma_f32_16x16x32_f16 v[104:107], v[184:187], v[144:147], v[104:107]
	v_mfma_f32_16x16x32_f16 v[84:87], v[176:179], v[152:155], v[84:87]
	v_mfma_f32_16x16x32_f16 v[80:83], v[184:187], v[152:155], v[80:83]
	v_mfma_f32_16x16x32_f16 v[68:71], v[176:179], v[168:171], v[68:71]
	v_mfma_f32_16x16x32_f16 v[64:67], v[184:187], v[168:171], v[64:67]
	v_mfma_f32_16x16x32_f16 v[140:143], v[180:183], v[136:139], v[140:143]
	v_mfma_f32_16x16x32_f16 v[128:131], v[184:187], v[128:131], v[132:135]
	v_mfma_f32_16x16x32_f16 v[112:115], v[180:183], v[148:151], v[112:115]
	v_mfma_f32_16x16x32_f16 v[104:107], v[188:191], v[148:151], v[104:107]
	v_mfma_f32_16x16x32_f16 v[84:87], v[180:183], v[164:167], v[84:87]
	v_mfma_f32_16x16x32_f16 v[80:83], v[188:191], v[164:167], v[80:83]
	v_mfma_f32_16x16x32_f16 v[68:71], v[180:183], v[172:175], v[68:71]
	v_mfma_f32_16x16x32_f16 v[64:67], v[188:191], v[172:175], v[64:67]
	v_mfma_f32_16x16x32_f16 v[128:131], v[188:191], v[136:139], v[128:131]
	s_mov_b32 m0, s23
	v_lshl_add_u64 v[196:197], s[28:29], 0, v[204:205]
	s_barrier
	ds_read_b128 v[132:135], v244 offset:16384
	ds_read_b128 v[136:139], v244 offset:17408
	ds_read_b128 v[144:147], v244 offset:18432
	ds_read_b128 v[148:151], v244 offset:19456
	ds_read_b128 v[152:155], v244 offset:20480
	ds_read_b128 v[164:167], v244 offset:21504
	ds_read_b128 v[168:171], v244 offset:22528
	ds_read_b128 v[172:175], v244 offset:23552
	global_load_lds_dwordx4 v[196:197], off
	v_lshl_add_u64 v[198:199], s[28:29], 0, v[208:209]
	s_mov_b32 m0, s45
	s_nop 0
	global_load_lds_dwordx4 v[198:199], off
	s_barrier
	s_waitcnt lgkmcnt(0)
	s_waitcnt lgkmcnt(0)
	v_mfma_f32_16x16x32_f16 v[60:63], v[88:91], v[132:135], v[60:63]
	v_mfma_f32_16x16x32_f16 v[56:59], v[108:111], v[132:135], v[56:59]
	v_mfma_f32_16x16x32_f16 v[44:47], v[88:91], v[144:147], v[44:47]
	v_mfma_f32_16x16x32_f16 v[40:43], v[108:111], v[144:147], v[40:43]
	v_mfma_f32_16x16x32_f16 v[28:31], v[88:91], v[152:155], v[28:31]
	v_mfma_f32_16x16x32_f16 v[24:27], v[108:111], v[152:155], v[24:27]
	v_mfma_f32_16x16x32_f16 v[12:15], v[88:91], v[168:171], v[12:15]
	v_mfma_f32_16x16x32_f16 v[8:11], v[108:111], v[168:171], v[8:11]
	v_mfma_f32_16x16x32_f16 v[60:63], v[96:99], v[136:139], v[60:63]
	v_mfma_f32_16x16x32_f16 v[56:59], v[116:119], v[136:139], v[56:59]
	v_mfma_f32_16x16x32_f16 v[44:47], v[96:99], v[148:151], v[44:47]
	v_mfma_f32_16x16x32_f16 v[40:43], v[116:119], v[148:151], v[40:43]
	v_mfma_f32_16x16x32_f16 v[28:31], v[96:99], v[164:167], v[28:31]
	v_mfma_f32_16x16x32_f16 v[24:27], v[116:119], v[164:167], v[24:27]
	v_mfma_f32_16x16x32_f16 v[12:15], v[96:99], v[172:175], v[12:15]
	v_mfma_f32_16x16x32_f16 v[8:11], v[116:119], v[172:175], v[8:11]
	s_barrier
	s_add_u32 s66, s26, 0x80000
	s_addc_u32 s67, s27, 0
	s_add_i32 s65, s60, s44
	v_lshl_add_u64 v[88:89], s[66:67], 0, v[206:207]
	s_mov_b32 m0, s65
	s_nop 0
	global_load_lds_dwordx4 v[88:89], off
	v_lshl_add_u64 v[88:89], s[66:67], 0, v[210:211]
	s_add_i32 m0, s65, 0x2000
	s_nop 0
	global_load_lds_dwordx4 v[88:89], off
	s_waitcnt vmcnt(6)
	s_barrier
	v_mfma_f32_16x16x32_f16 v[52:55], v[176:179], v[132:135], v[52:55]
	v_mfma_f32_16x16x32_f16 v[48:51], v[184:187], v[132:135], v[48:51]
	v_mfma_f32_16x16x32_f16 v[36:39], v[176:179], v[144:147], v[36:39]
	v_mfma_f32_16x16x32_f16 v[32:35], v[184:187], v[144:147], v[32:35]
	v_mfma_f32_16x16x32_f16 v[20:23], v[176:179], v[152:155], v[20:23]
	v_mfma_f32_16x16x32_f16 v[16:19], v[184:187], v[152:155], v[16:19]
	v_mfma_f32_16x16x32_f16 v[4:7], v[176:179], v[168:171], v[4:7]
	v_mfma_f32_16x16x32_f16 v[0:3], v[184:187], v[168:171], v[0:3]
	v_mfma_f32_16x16x32_f16 v[52:55], v[180:183], v[136:139], v[52:55]
	v_mfma_f32_16x16x32_f16 v[48:51], v[188:191], v[136:139], v[48:51]
	v_mfma_f32_16x16x32_f16 v[36:39], v[180:183], v[148:151], v[36:39]
	v_mfma_f32_16x16x32_f16 v[32:35], v[188:191], v[148:151], v[32:35]
	v_mfma_f32_16x16x32_f16 v[20:23], v[180:183], v[164:167], v[20:23]
	v_mfma_f32_16x16x32_f16 v[16:19], v[188:191], v[164:167], v[16:19]
	v_mfma_f32_16x16x32_f16 v[4:7], v[180:183], v[172:175], v[4:7]
	v_mfma_f32_16x16x32_f16 v[0:3], v[188:191], v[172:175], v[0:3]
	s_add_i32 s65, 0, 0x18000
	v_add_u32_e32 v116, s65, v241
	s_barrier
	ds_read_b128 v[88:91], v116
	ds_read_b128 v[96:99], v116 offset:1024
	ds_read_b128 v[108:111], v116 offset:2048
	ds_read_b128 v[116:119], v116 offset:3072
	s_add_u32 s28, s28, 0x80000
	s_addc_u32 s29, s29, 0
	s_mov_b32 m0, s48
	v_lshl_add_u64 v[176:177], s[28:29], 0, v[204:205]
	ds_read_b128 v[132:135], v244 offset:32768
	ds_read_b128 v[136:139], v244 offset:33792
	ds_read_b128 v[144:147], v244 offset:34816
	ds_read_b128 v[148:151], v244 offset:35840
	ds_read_b128 v[152:155], v244 offset:36864
	ds_read_b128 v[164:167], v244 offset:37888
	ds_read_b128 v[168:171], v244 offset:38912
	ds_read_b128 v[172:175], v244 offset:39936
	global_load_lds_dwordx4 v[176:177], off
	v_lshl_add_u64 v[176:177], s[28:29], 0, v[208:209]
	s_mov_b32 m0, s49
	s_nop 0
	global_load_lds_dwordx4 v[176:177], off
	s_waitcnt lgkmcnt(8)
	s_barrier
	s_waitcnt lgkmcnt(0)
	s_waitcnt lgkmcnt(0)
	v_mfma_f32_16x16x32_f16 v[160:163], v[88:91], v[132:135], v[160:163]
	v_mfma_f32_16x16x32_f16 v[156:159], v[108:111], v[132:135], v[156:159]
	v_mfma_f32_16x16x32_f16 v[124:127], v[88:91], v[144:147], v[124:127]
	v_mfma_f32_16x16x32_f16 v[120:123], v[108:111], v[144:147], v[120:123]
	v_mfma_f32_16x16x32_f16 v[100:103], v[88:91], v[152:155], v[100:103]
	v_mfma_f32_16x16x32_f16 v[92:95], v[108:111], v[152:155], v[92:95]
	v_mfma_f32_16x16x32_f16 v[76:79], v[88:91], v[168:171], v[76:79]
	v_mfma_f32_16x16x32_f16 v[72:75], v[108:111], v[168:171], v[72:75]
	v_mfma_f32_16x16x32_f16 v[160:163], v[96:99], v[136:139], v[160:163]
	v_mfma_f32_16x16x32_f16 v[156:159], v[116:119], v[136:139], v[156:159]
	v_mfma_f32_16x16x32_f16 v[124:127], v[96:99], v[148:151], v[124:127]
	v_mfma_f32_16x16x32_f16 v[120:123], v[116:119], v[148:151], v[120:123]
	v_mfma_f32_16x16x32_f16 v[100:103], v[96:99], v[164:167], v[100:103]
	v_mfma_f32_16x16x32_f16 v[92:95], v[116:119], v[164:167], v[92:95]
	v_mfma_f32_16x16x32_f16 v[76:79], v[96:99], v[172:175], v[76:79]
	v_mfma_f32_16x16x32_f16 v[72:75], v[116:119], v[172:175], v[72:75]
	s_barrier
	s_add_i32 s28, 0, 0x1c000
	s_add_i32 s29, s65, s44
	v_add_u32_e32 v188, s28, v241
	v_lshl_add_u64 v[192:193], v[192:193], 0, s[6:7]
	s_mov_b32 m0, s29
	ds_read_b128 v[176:179], v188
	ds_read_b128 v[180:183], v188 offset:1024
	ds_read_b128 v[184:187], v188 offset:2048
	ds_read_b128 v[188:191], v188 offset:3072
	global_load_lds_dwordx4 v[192:193], off
	v_lshl_add_u64 v[192:193], v[194:195], 0, s[6:7]
	s_add_i32 m0, s29, 0x2000
	s_nop 0
	global_load_lds_dwordx4 v[192:193], off
	s_barrier
	s_waitcnt lgkmcnt(0)
	s_waitcnt lgkmcnt(0)
	v_mfma_f32_16x16x32_f16 v[140:143], v[176:179], v[132:135], v[140:143]
	v_mfma_f32_16x16x32_f16 v[128:131], v[184:187], v[132:135], v[128:131]
	v_mfma_f32_16x16x32_f16 v[112:115], v[176:179], v[144:147], v[112:115]
	v_mfma_f32_16x16x32_f16 v[104:107], v[184:187], v[144:147], v[104:107]
	v_mfma_f32_16x16x32_f16 v[84:87], v[176:179], v[152:155], v[84:87]
	v_mfma_f32_16x16x32_f16 v[80:83], v[184:187], v[152:155], v[80:83]
	v_mfma_f32_16x16x32_f16 v[68:71], v[176:179], v[168:171], v[68:71]
	v_mfma_f32_16x16x32_f16 v[64:67], v[184:187], v[168:171], v[64:67]
	v_mfma_f32_16x16x32_f16 v[140:143], v[180:183], v[136:139], v[140:143]
	v_mfma_f32_16x16x32_f16 v[132:135], v[188:191], v[136:139], v[128:131]
	v_mfma_f32_16x16x32_f16 v[112:115], v[180:183], v[148:151], v[112:115]
	v_mfma_f32_16x16x32_f16 v[104:107], v[188:191], v[148:151], v[104:107]
	v_mfma_f32_16x16x32_f16 v[84:87], v[180:183], v[164:167], v[84:87]
	v_mfma_f32_16x16x32_f16 v[80:83], v[188:191], v[164:167], v[80:83]
	v_mfma_f32_16x16x32_f16 v[68:71], v[180:183], v[172:175], v[68:71]
	v_mfma_f32_16x16x32_f16 v[64:67], v[188:191], v[172:175], v[64:67]
	s_mov_b32 m0, s51
	v_lshl_add_u64 v[192:193], v[196:197], 0, s[6:7]
	s_barrier
	ds_read_b128 v[128:131], v244 offset:49152
	ds_read_b128 v[136:139], v244 offset:50176
	ds_read_b128 v[144:147], v244 offset:51200
	ds_read_b128 v[148:151], v244 offset:52224
	ds_read_b128 v[152:155], v244 offset:53248
	ds_read_b128 v[164:167], v244 offset:54272
	ds_read_b128 v[168:171], v244 offset:55296
	ds_read_b128 v[172:175], v244 offset:56320
	global_load_lds_dwordx4 v[192:193], off
	v_lshl_add_u64 v[192:193], v[198:199], 0, s[6:7]
	s_mov_b32 m0, s54
	s_nop 0
	global_load_lds_dwordx4 v[192:193], off
	s_barrier
	s_waitcnt lgkmcnt(0)
	s_waitcnt lgkmcnt(0)
	v_mfma_f32_16x16x32_f16 v[60:63], v[88:91], v[128:131], v[60:63]
	v_mfma_f32_16x16x32_f16 v[56:59], v[108:111], v[128:131], v[56:59]
	v_mfma_f32_16x16x32_f16 v[44:47], v[88:91], v[144:147], v[44:47]
	v_mfma_f32_16x16x32_f16 v[40:43], v[108:111], v[144:147], v[40:43]
	v_mfma_f32_16x16x32_f16 v[28:31], v[88:91], v[152:155], v[28:31]
	v_mfma_f32_16x16x32_f16 v[24:27], v[108:111], v[152:155], v[24:27]
	v_mfma_f32_16x16x32_f16 v[12:15], v[88:91], v[168:171], v[12:15]
	v_mfma_f32_16x16x32_f16 v[8:11], v[108:111], v[168:171], v[8:11]
	v_mfma_f32_16x16x32_f16 v[60:63], v[96:99], v[136:139], v[60:63]
	v_mfma_f32_16x16x32_f16 v[56:59], v[116:119], v[136:139], v[56:59]
	v_mfma_f32_16x16x32_f16 v[44:47], v[96:99], v[148:151], v[44:47]
	v_mfma_f32_16x16x32_f16 v[40:43], v[116:119], v[148:151], v[40:43]
	v_mfma_f32_16x16x32_f16 v[28:31], v[96:99], v[164:167], v[28:31]
	v_mfma_f32_16x16x32_f16 v[24:27], v[116:119], v[164:167], v[24:27]
	v_mfma_f32_16x16x32_f16 v[12:15], v[96:99], v[172:175], v[12:15]
	v_mfma_f32_16x16x32_f16 v[8:11], v[116:119], v[172:175], v[8:11]
	s_barrier
	s_add_u32 s26, s26, 0x80080
	s_addc_u32 s27, s27, 0
	s_add_i32 s28, s28, s44
	v_lshl_add_u64 v[88:89], s[26:27], 0, v[206:207]
	s_mov_b32 m0, s28
	s_nop 0
	global_load_lds_dwordx4 v[88:89], off
	v_lshl_add_u64 v[88:89], s[26:27], 0, v[210:211]
	s_add_i32 m0, s28, 0x2000
	s_nop 0
	global_load_lds_dwordx4 v[88:89], off
	s_waitcnt vmcnt(6)
	s_barrier
	v_mfma_f32_16x16x32_f16 v[52:55], v[176:179], v[128:131], v[52:55]
	v_mfma_f32_16x16x32_f16 v[48:51], v[184:187], v[128:131], v[48:51]
	v_mfma_f32_16x16x32_f16 v[36:39], v[176:179], v[144:147], v[36:39]
	v_mfma_f32_16x16x32_f16 v[32:35], v[184:187], v[144:147], v[32:35]
	v_mfma_f32_16x16x32_f16 v[20:23], v[176:179], v[152:155], v[20:23]
	v_mfma_f32_16x16x32_f16 v[16:19], v[184:187], v[152:155], v[16:19]
	v_mfma_f32_16x16x32_f16 v[4:7], v[176:179], v[168:171], v[4:7]
	v_mfma_f32_16x16x32_f16 v[0:3], v[184:187], v[168:171], v[0:3]
	v_mfma_f32_16x16x32_f16 v[52:55], v[180:183], v[136:139], v[52:55]
	v_mfma_f32_16x16x32_f16 v[48:51], v[188:191], v[136:139], v[48:51]
	v_mfma_f32_16x16x32_f16 v[36:39], v[180:183], v[148:151], v[36:39]
	v_mfma_f32_16x16x32_f16 v[32:35], v[188:191], v[148:151], v[32:35]
	v_mfma_f32_16x16x32_f16 v[20:23], v[180:183], v[164:167], v[20:23]
	v_mfma_f32_16x16x32_f16 v[16:19], v[188:191], v[164:167], v[16:19]
	v_mfma_f32_16x16x32_f16 v[4:7], v[180:183], v[172:175], v[4:7]
	v_mfma_f32_16x16x32_f16 v[0:3], v[188:191], v[172:175], v[0:3]
	s_add_i32 s64, s64, 2
	s_add_u32 s24, s24, 0x100
	s_addc_u32 s25, s25, 0
	s_add_u32 s62, s62, 0x100
	s_addc_u32 s63, s63, 0
	s_cmp_gt_u32 s64, 29
	s_barrier
	s_cbranch_scc0 .LBB0_1185
	s_setprio 0
	s_lshl_b32 s15, s22, 8
	s_add_i32 s17, s15, 0xffffe000
	s_lshr_b32 s17, s17, 11
	s_mulk_i32 s17, 0x1800
	s_addk_i32 s17, 0x1800
	s_cmp_gt_i32 s22, 31
	s_cselect_b32 s24, s17, 0
	s_ashr_i32 s25, s24, 31
	v_lshl_or_b32 v128, s30, 8, v242
	s_lshl_b64 s[24:25], s[24:25], 2
	s_add_u32 s24, s42, s24
	v_ashrrev_i32_e32 v129, 31, v128
	v_add_u32_e32 v130, s15, v240
	s_addc_u32 s25, s43, s25
	v_lshlrev_b64 v[220:221], 1, v[128:129]
	v_ashrrev_i32_e32 v131, 31, v130
	v_lshl_add_u64 v[96:97], v[128:129], 2, s[24:25]
	v_lshl_add_u64 v[128:129], s[4:5], 0, v[220:221]
	v_lshlrev_b64 v[236:237], 12, v[130:131]
	v_lshl_add_u64 v[136:137], v[128:129], 0, v[236:237]
	global_load_dwordx4 v[108:111], v[96:97], off offset:16
	global_load_dwordx4 v[116:119], v[96:97], off
	global_load_dwordx4 v[88:91], v[96:97], off offset:528
	s_nop 0
	global_load_dwordx4 v[96:99], v[96:97], off offset:512
	s_nop 0
	global_load_dwordx4 v[246:249], v[136:137], off nt
	global_load_dwordx4 v[200:203], v[136:137], off offset:256 nt
	v_or_b32_e32 v136, 16, v130
	v_ashrrev_i32_e32 v137, 31, v136
	v_lshlrev_b64 v[234:235], 12, v[136:137]
	v_lshl_add_u64 v[136:137], v[128:129], 0, v[234:235]
	global_load_dwordx4 v[196:199], v[136:137], off nt
	global_load_dwordx4 v[192:195], v[136:137], off offset:256 nt
	v_or_b32_e32 v136, 32, v130
	v_ashrrev_i32_e32 v137, 31, v136
	v_lshlrev_b64 v[232:233], 12, v[136:137]
	v_lshl_add_u64 v[136:137], v[128:129], 0, v[232:233]
	global_load_dwordx4 v[188:191], v[136:137], off nt
	global_load_dwordx4 v[184:187], v[136:137], off offset:256 nt
	v_readlane_b32 s64, v254, 21
	v_readlane_b32 s68, v254, 25
	v_readlane_b32 s69, v254, 26
	s_mov_b64 s[56:57], s[68:69]
	v_or_b32_e32 v130, 48, v130
	v_ashrrev_i32_e32 v131, 31, v130
	v_lshlrev_b64 v[230:231], 12, v[130:131]
	v_lshl_add_u64 v[130:131], v[128:129], 0, v[230:231]
	global_load_dwordx4 v[180:183], v[130:131], off nt
	global_load_dwordx4 v[176:179], v[130:131], off offset:256 nt
	v_lshl_add_u64 v[228:229], v[236:237], 0, s[0:1]
	v_lshl_add_u64 v[130:131], v[128:129], 0, v[228:229]
	global_load_dwordx4 v[172:175], v[130:131], off nt
	global_load_dwordx4 v[168:171], v[130:131], off offset:256 nt
	v_lshl_add_u64 v[226:227], v[236:237], 0, s[8:9]
	v_lshl_add_u64 v[130:131], v[128:129], 0, v[226:227]
	global_load_dwordx4 v[164:167], v[130:131], off nt
	global_load_dwordx4 v[152:155], v[130:131], off offset:256 nt
	v_lshl_add_u64 v[224:225], v[236:237], 0, s[10:11]
	v_lshl_add_u64 v[130:131], v[128:129], 0, v[224:225]
	global_load_dwordx4 v[148:151], v[130:131], off nt
	global_load_dwordx4 v[144:147], v[130:131], off offset:256 nt
	v_lshl_add_u64 v[222:223], v[236:237], 0, s[12:13]
	v_lshl_add_u64 v[128:129], v[128:129], 0, v[222:223]
	global_load_dwordx4 v[136:139], v[128:129], off nt
	s_nop 0
	global_load_dwordx4 v[128:131], v[128:129], off offset:256 nt
	s_and_b64 vcc, exec, s[2:3]
	s_mov_b32 s30, s14
	s_mov_b32 s22, s16
	s_mov_b64 s[26:27], s[20:21]
	s_mov_b64 s[24:25], s[18:19]
	v_readlane_b32 s65, v254, 22
	v_readlane_b32 s66, v254, 23
	v_readlane_b32 s67, v254, 24
	v_readlane_b32 s70, v254, 27
	v_readlane_b32 s71, v254, 28
	v_readlane_b32 s72, v254, 29
	v_readlane_b32 s73, v254, 30
	v_readlane_b32 s74, v254, 31
	v_readlane_b32 s75, v254, 32
	v_readlane_b32 s76, v254, 33
	v_readlane_b32 s77, v254, 34
	v_readlane_b32 s78, v254, 35
	v_readlane_b32 s79, v254, 36
	s_waitcnt vmcnt(0)
	v_cvt_f32_f16_e32 v250, v246
	v_cvt_f32_f16_sdwa v251, v246 dst_sel:DWORD dst_unused:UNUSED_PAD src0_sel:WORD_1
	v_pk_fma_f32 v[160:161], v[160:161], v[116:117], v[250:251]
	s_nop 0
	v_cvt_pk_f16_f32 v246, v160, v161
	v_cvt_f32_f16_e32 v160, v248
	v_cvt_f32_f16_sdwa v161, v248 dst_sel:DWORD dst_unused:UNUSED_PAD src0_sel:WORD_1
	v_pk_fma_f32 v[156:157], v[156:157], v[108:109], v[160:161]
	s_nop 0
	v_cvt_pk_f16_f32 v248, v156, v157
	v_cvt_f32_f16_e32 v156, v247
	v_cvt_f32_f16_sdwa v157, v247 dst_sel:DWORD dst_unused:UNUSED_PAD src0_sel:WORD_1
	v_pk_fma_f32 v[156:157], v[162:163], v[118:119], v[156:157]
	s_nop 0
	v_cvt_pk_f16_f32 v247, v156, v157
	v_cvt_f32_f16_e32 v156, v249
	v_cvt_f32_f16_sdwa v157, v249 dst_sel:DWORD dst_unused:UNUSED_PAD src0_sel:WORD_1
	v_pk_fma_f32 v[156:157], v[158:159], v[110:111], v[156:157]
	s_nop 0
	v_cvt_pk_f16_f32 v249, v156, v157
	v_lshl_add_u64 v[156:157], s[56:57], 0, v[236:237]
	v_lshl_add_u64 v[160:161], v[156:157], 0, v[220:221]
	v_cvt_f32_f16_e32 v156, v200
	v_cvt_f32_f16_sdwa v157, v200 dst_sel:DWORD dst_unused:UNUSED_PAD src0_sel:WORD_1
	global_store_dwordx4 v[160:161], v[246:249], off
	v_pk_fma_f32 v[140:141], v[140:141], v[96:97], v[156:157]
	s_nop 0
	v_cvt_pk_f16_f32 v156, v140, v141
	v_cvt_f32_f16_e32 v140, v202
	v_cvt_f32_f16_sdwa v141, v202 dst_sel:DWORD dst_unused:UNUSED_PAD src0_sel:WORD_1
	v_pk_fma_f32 v[132:133], v[132:133], v[88:89], v[140:141]
	s_nop 0
	v_cvt_pk_f16_f32 v158, v132, v133
	v_cvt_f32_f16_e32 v132, v201
	v_cvt_f32_f16_sdwa v133, v201 dst_sel:DWORD dst_unused:UNUSED_PAD src0_sel:WORD_1
	v_pk_fma_f32 v[132:133], v[142:143], v[98:99], v[132:133]
	s_nop 0
	v_cvt_pk_f16_f32 v157, v132, v133
	v_cvt_f32_f16_e32 v132, v203
	v_cvt_f32_f16_sdwa v133, v203 dst_sel:DWORD dst_unused:UNUSED_PAD src0_sel:WORD_1
	v_pk_fma_f32 v[132:133], v[134:135], v[90:91], v[132:133]
	s_nop 0
	v_cvt_pk_f16_f32 v159, v132, v133
	v_cvt_f32_f16_e32 v132, v196
	v_cvt_f32_f16_sdwa v133, v196 dst_sel:DWORD dst_unused:UNUSED_PAD src0_sel:WORD_1
	global_store_dwordx4 v[160:161], v[156:159], off offset:256
	v_pk_fma_f32 v[124:125], v[124:125], v[116:117], v[132:133]
	s_nop 0
	v_cvt_pk_f16_f32 v132, v124, v125
	v_cvt_f32_f16_e32 v124, v198
	v_cvt_f32_f16_sdwa v125, v198 dst_sel:DWORD dst_unused:UNUSED_PAD src0_sel:WORD_1
	v_pk_fma_f32 v[120:121], v[120:121], v[108:109], v[124:125]
	s_nop 0
	v_cvt_pk_f16_f32 v134, v120, v121
	v_cvt_f32_f16_e32 v120, v197
	v_cvt_f32_f16_sdwa v121, v197 dst_sel:DWORD dst_unused:UNUSED_PAD src0_sel:WORD_1
	v_pk_fma_f32 v[120:121], v[126:127], v[118:119], v[120:121]
	s_nop 0
	v_cvt_pk_f16_f32 v133, v120, v121
	v_cvt_f32_f16_e32 v120, v199
	v_cvt_f32_f16_sdwa v121, v199 dst_sel:DWORD dst_unused:UNUSED_PAD src0_sel:WORD_1
	v_pk_fma_f32 v[120:121], v[122:123], v[110:111], v[120:121]
	s_nop 0
	v_cvt_pk_f16_f32 v135, v120, v121
	v_lshl_add_u64 v[120:121], s[56:57], 0, v[234:235]
	v_lshl_add_u64 v[124:125], v[120:121], 0, v[220:221]
	v_cvt_f32_f16_e32 v120, v192
	v_cvt_f32_f16_sdwa v121, v192 dst_sel:DWORD dst_unused:UNUSED_PAD src0_sel:WORD_1
	global_store_dwordx4 v[124:125], v[132:135], off
	v_pk_fma_f32 v[112:113], v[112:113], v[96:97], v[120:121]
	s_nop 0
	v_cvt_pk_f16_f32 v120, v112, v113
	v_cvt_f32_f16_e32 v112, v194
	v_cvt_f32_f16_sdwa v113, v194 dst_sel:DWORD dst_unused:UNUSED_PAD src0_sel:WORD_1
	v_pk_fma_f32 v[104:105], v[104:105], v[88:89], v[112:113]
	s_nop 0
	v_cvt_pk_f16_f32 v122, v104, v105
	v_cvt_f32_f16_e32 v104, v193
	v_cvt_f32_f16_sdwa v105, v193 dst_sel:DWORD dst_unused:UNUSED_PAD src0_sel:WORD_1
	v_pk_fma_f32 v[104:105], v[114:115], v[98:99], v[104:105]
	s_nop 0
	v_cvt_pk_f16_f32 v121, v104, v105
	v_cvt_f32_f16_e32 v104, v195
	v_cvt_f32_f16_sdwa v105, v195 dst_sel:DWORD dst_unused:UNUSED_PAD src0_sel:WORD_1
	v_pk_fma_f32 v[104:105], v[106:107], v[90:91], v[104:105]
	s_nop 0
	v_cvt_pk_f16_f32 v123, v104, v105
	v_cvt_f32_f16_e32 v104, v188
	v_cvt_f32_f16_sdwa v105, v188 dst_sel:DWORD dst_unused:UNUSED_PAD src0_sel:WORD_1
	global_store_dwordx4 v[124:125], v[120:123], off offset:256
	v_pk_fma_f32 v[100:101], v[100:101], v[116:117], v[104:105]
	s_nop 0
	v_cvt_pk_f16_f32 v104, v100, v101
	v_cvt_f32_f16_e32 v100, v190
	v_cvt_f32_f16_sdwa v101, v190 dst_sel:DWORD dst_unused:UNUSED_PAD src0_sel:WORD_1
	v_pk_fma_f32 v[92:93], v[92:93], v[108:109], v[100:101]
	s_nop 0
	v_cvt_pk_f16_f32 v106, v92, v93
	v_cvt_f32_f16_e32 v92, v189
	v_cvt_f32_f16_sdwa v93, v189 dst_sel:DWORD dst_unused:UNUSED_PAD src0_sel:WORD_1
	v_pk_fma_f32 v[92:93], v[102:103], v[118:119], v[92:93]
	s_nop 0
	v_cvt_pk_f16_f32 v105, v92, v93
	v_cvt_f32_f16_e32 v92, v191
	v_cvt_f32_f16_sdwa v93, v191 dst_sel:DWORD dst_unused:UNUSED_PAD src0_sel:WORD_1
	v_pk_fma_f32 v[92:93], v[94:95], v[110:111], v[92:93]
	s_nop 0
	v_cvt_pk_f16_f32 v107, v92, v93
	v_lshl_add_u64 v[92:93], s[56:57], 0, v[232:233]
	v_lshl_add_u64 v[100:101], v[92:93], 0, v[220:221]
	v_cvt_f32_f16_e32 v92, v184
	v_cvt_f32_f16_sdwa v93, v184 dst_sel:DWORD dst_unused:UNUSED_PAD src0_sel:WORD_1
	global_store_dwordx4 v[100:101], v[104:107], off
	v_pk_fma_f32 v[84:85], v[84:85], v[96:97], v[92:93]
	s_nop 0
	v_cvt_pk_f16_f32 v92, v84, v85
	v_cvt_f32_f16_e32 v84, v186
	v_cvt_f32_f16_sdwa v85, v186 dst_sel:DWORD dst_unused:UNUSED_PAD src0_sel:WORD_1
	v_pk_fma_f32 v[80:81], v[80:81], v[88:89], v[84:85]
	s_nop 0
	v_cvt_pk_f16_f32 v94, v80, v81
	v_cvt_f32_f16_e32 v80, v185
	v_cvt_f32_f16_sdwa v81, v185 dst_sel:DWORD dst_unused:UNUSED_PAD src0_sel:WORD_1
	v_pk_fma_f32 v[80:81], v[86:87], v[98:99], v[80:81]
	s_nop 0
	v_cvt_pk_f16_f32 v93, v80, v81
	v_cvt_f32_f16_e32 v80, v187
	v_cvt_f32_f16_sdwa v81, v187 dst_sel:DWORD dst_unused:UNUSED_PAD src0_sel:WORD_1
	v_pk_fma_f32 v[80:81], v[82:83], v[90:91], v[80:81]
	s_nop 0
	v_cvt_pk_f16_f32 v95, v80, v81
	v_cvt_f32_f16_e32 v80, v180
	v_cvt_f32_f16_sdwa v81, v180 dst_sel:DWORD dst_unused:UNUSED_PAD src0_sel:WORD_1
	global_store_dwordx4 v[100:101], v[92:95], off offset:256
	v_pk_fma_f32 v[76:77], v[76:77], v[116:117], v[80:81]
	s_nop 0
	v_cvt_pk_f16_f32 v80, v76, v77
	v_cvt_f32_f16_e32 v76, v182
	v_cvt_f32_f16_sdwa v77, v182 dst_sel:DWORD dst_unused:UNUSED_PAD src0_sel:WORD_1
	v_pk_fma_f32 v[72:73], v[72:73], v[108:109], v[76:77]
	s_nop 0
	v_cvt_pk_f16_f32 v82, v72, v73
	v_cvt_f32_f16_e32 v72, v181
	v_cvt_f32_f16_sdwa v73, v181 dst_sel:DWORD dst_unused:UNUSED_PAD src0_sel:WORD_1
	v_pk_fma_f32 v[72:73], v[78:79], v[118:119], v[72:73]
	s_nop 0
	v_cvt_pk_f16_f32 v81, v72, v73
	v_cvt_f32_f16_e32 v72, v183
	v_cvt_f32_f16_sdwa v73, v183 dst_sel:DWORD dst_unused:UNUSED_PAD src0_sel:WORD_1
	v_pk_fma_f32 v[72:73], v[74:75], v[110:111], v[72:73]
	s_nop 0
	v_cvt_pk_f16_f32 v83, v72, v73
	v_lshl_add_u64 v[72:73], s[56:57], 0, v[230:231]
	v_lshl_add_u64 v[76:77], v[72:73], 0, v[220:221]
	v_cvt_f32_f16_e32 v72, v176
	v_cvt_f32_f16_sdwa v73, v176 dst_sel:DWORD dst_unused:UNUSED_PAD src0_sel:WORD_1
	global_store_dwordx4 v[76:77], v[80:83], off
	v_pk_fma_f32 v[68:69], v[68:69], v[96:97], v[72:73]
	s_nop 0
	v_cvt_pk_f16_f32 v72, v68, v69
	v_cvt_f32_f16_e32 v68, v178
	v_cvt_f32_f16_sdwa v69, v178 dst_sel:DWORD dst_unused:UNUSED_PAD src0_sel:WORD_1
	v_pk_fma_f32 v[64:65], v[64:65], v[88:89], v[68:69]
	s_nop 0
	v_cvt_pk_f16_f32 v74, v64, v65
	v_cvt_f32_f16_e32 v64, v177
	v_cvt_f32_f16_sdwa v65, v177 dst_sel:DWORD dst_unused:UNUSED_PAD src0_sel:WORD_1
	v_pk_fma_f32 v[64:65], v[70:71], v[98:99], v[64:65]
	s_nop 0
	v_cvt_pk_f16_f32 v73, v64, v65
	v_cvt_f32_f16_e32 v64, v179
	v_cvt_f32_f16_sdwa v65, v179 dst_sel:DWORD dst_unused:UNUSED_PAD src0_sel:WORD_1
	v_pk_fma_f32 v[64:65], v[66:67], v[90:91], v[64:65]
	s_nop 0
	v_cvt_pk_f16_f32 v75, v64, v65
	v_cvt_f32_f16_e32 v64, v172
	v_cvt_f32_f16_sdwa v65, v172 dst_sel:DWORD dst_unused:UNUSED_PAD src0_sel:WORD_1
	global_store_dwordx4 v[76:77], v[72:75], off offset:256
	v_pk_fma_f32 v[60:61], v[60:61], v[116:117], v[64:65]
	s_nop 0
	v_cvt_pk_f16_f32 v64, v60, v61
	v_cvt_f32_f16_e32 v60, v174
	v_cvt_f32_f16_sdwa v61, v174 dst_sel:DWORD dst_unused:UNUSED_PAD src0_sel:WORD_1
	v_pk_fma_f32 v[56:57], v[56:57], v[108:109], v[60:61]
	s_nop 0
	v_cvt_pk_f16_f32 v66, v56, v57
	v_cvt_f32_f16_e32 v56, v173
	v_cvt_f32_f16_sdwa v57, v173 dst_sel:DWORD dst_unused:UNUSED_PAD src0_sel:WORD_1
	v_pk_fma_f32 v[56:57], v[62:63], v[118:119], v[56:57]
	s_nop 0
	v_cvt_pk_f16_f32 v65, v56, v57
	v_cvt_f32_f16_e32 v56, v175
	v_cvt_f32_f16_sdwa v57, v175 dst_sel:DWORD dst_unused:UNUSED_PAD src0_sel:WORD_1
	v_pk_fma_f32 v[56:57], v[58:59], v[110:111], v[56:57]
	s_nop 0
	v_cvt_pk_f16_f32 v67, v56, v57
	v_lshl_add_u64 v[56:57], s[56:57], 0, v[228:229]
	v_lshl_add_u64 v[60:61], v[56:57], 0, v[220:221]
	v_cvt_f32_f16_e32 v56, v168
	v_cvt_f32_f16_sdwa v57, v168 dst_sel:DWORD dst_unused:UNUSED_PAD src0_sel:WORD_1
	global_store_dwordx4 v[60:61], v[64:67], off
	v_pk_fma_f32 v[52:53], v[52:53], v[96:97], v[56:57]
	s_nop 0
	v_cvt_pk_f16_f32 v56, v52, v53
	v_cvt_f32_f16_e32 v52, v170
	v_cvt_f32_f16_sdwa v53, v170 dst_sel:DWORD dst_unused:UNUSED_PAD src0_sel:WORD_1
	v_pk_fma_f32 v[48:49], v[48:49], v[88:89], v[52:53]
	s_nop 0
	v_cvt_pk_f16_f32 v58, v48, v49
	v_cvt_f32_f16_e32 v48, v169
	v_cvt_f32_f16_sdwa v49, v169 dst_sel:DWORD dst_unused:UNUSED_PAD src0_sel:WORD_1
	v_pk_fma_f32 v[48:49], v[54:55], v[98:99], v[48:49]
	s_nop 0
	v_cvt_pk_f16_f32 v57, v48, v49
	v_cvt_f32_f16_e32 v48, v171
	v_cvt_f32_f16_sdwa v49, v171 dst_sel:DWORD dst_unused:UNUSED_PAD src0_sel:WORD_1
	v_pk_fma_f32 v[48:49], v[50:51], v[90:91], v[48:49]
	s_nop 0
	v_cvt_pk_f16_f32 v59, v48, v49
	v_cvt_f32_f16_e32 v48, v164
	v_cvt_f32_f16_sdwa v49, v164 dst_sel:DWORD dst_unused:UNUSED_PAD src0_sel:WORD_1
	global_store_dwordx4 v[60:61], v[56:59], off offset:256
	v_pk_fma_f32 v[44:45], v[44:45], v[116:117], v[48:49]
	s_nop 0
	v_cvt_pk_f16_f32 v48, v44, v45
	v_cvt_f32_f16_e32 v44, v166
	v_cvt_f32_f16_sdwa v45, v166 dst_sel:DWORD dst_unused:UNUSED_PAD src0_sel:WORD_1
	v_pk_fma_f32 v[40:41], v[40:41], v[108:109], v[44:45]
	s_nop 0
	v_cvt_pk_f16_f32 v50, v40, v41
	v_cvt_f32_f16_e32 v40, v165
	v_cvt_f32_f16_sdwa v41, v165 dst_sel:DWORD dst_unused:UNUSED_PAD src0_sel:WORD_1
	v_pk_fma_f32 v[40:41], v[46:47], v[118:119], v[40:41]
	s_nop 0
	v_cvt_pk_f16_f32 v49, v40, v41
	v_cvt_f32_f16_e32 v40, v167
	v_cvt_f32_f16_sdwa v41, v167 dst_sel:DWORD dst_unused:UNUSED_PAD src0_sel:WORD_1
	v_pk_fma_f32 v[40:41], v[42:43], v[110:111], v[40:41]
	s_nop 0
	v_cvt_pk_f16_f32 v51, v40, v41
	v_lshl_add_u64 v[40:41], s[56:57], 0, v[226:227]
	v_lshl_add_u64 v[44:45], v[40:41], 0, v[220:221]
	v_cvt_f32_f16_e32 v40, v152
	v_cvt_f32_f16_sdwa v41, v152 dst_sel:DWORD dst_unused:UNUSED_PAD src0_sel:WORD_1
	global_store_dwordx4 v[44:45], v[48:51], off
	v_pk_fma_f32 v[36:37], v[36:37], v[96:97], v[40:41]
	s_nop 0
	v_cvt_pk_f16_f32 v40, v36, v37
	v_cvt_f32_f16_e32 v36, v154
	v_cvt_f32_f16_sdwa v37, v154 dst_sel:DWORD dst_unused:UNUSED_PAD src0_sel:WORD_1
	v_pk_fma_f32 v[32:33], v[32:33], v[88:89], v[36:37]
	s_nop 0
	v_cvt_pk_f16_f32 v42, v32, v33
	v_cvt_f32_f16_e32 v32, v153
	v_cvt_f32_f16_sdwa v33, v153 dst_sel:DWORD dst_unused:UNUSED_PAD src0_sel:WORD_1
	v_pk_fma_f32 v[32:33], v[38:39], v[98:99], v[32:33]
	s_nop 0
	v_cvt_pk_f16_f32 v41, v32, v33
	v_cvt_f32_f16_e32 v32, v155
	v_cvt_f32_f16_sdwa v33, v155 dst_sel:DWORD dst_unused:UNUSED_PAD src0_sel:WORD_1
	v_pk_fma_f32 v[32:33], v[34:35], v[90:91], v[32:33]
	s_nop 0
	v_cvt_pk_f16_f32 v43, v32, v33
	v_cvt_f32_f16_e32 v32, v148
	v_cvt_f32_f16_sdwa v33, v148 dst_sel:DWORD dst_unused:UNUSED_PAD src0_sel:WORD_1
	global_store_dwordx4 v[44:45], v[40:43], off offset:256
	v_pk_fma_f32 v[28:29], v[28:29], v[116:117], v[32:33]
	s_nop 0
	v_cvt_pk_f16_f32 v32, v28, v29
	v_cvt_f32_f16_e32 v28, v150
	v_cvt_f32_f16_sdwa v29, v150 dst_sel:DWORD dst_unused:UNUSED_PAD src0_sel:WORD_1
	v_pk_fma_f32 v[24:25], v[24:25], v[108:109], v[28:29]
	s_nop 0
	v_cvt_pk_f16_f32 v34, v24, v25
	v_cvt_f32_f16_e32 v24, v149
	v_cvt_f32_f16_sdwa v25, v149 dst_sel:DWORD dst_unused:UNUSED_PAD src0_sel:WORD_1
	v_pk_fma_f32 v[24:25], v[30:31], v[118:119], v[24:25]
	s_nop 0
	v_cvt_pk_f16_f32 v33, v24, v25
	v_cvt_f32_f16_e32 v24, v151
	v_cvt_f32_f16_sdwa v25, v151 dst_sel:DWORD dst_unused:UNUSED_PAD src0_sel:WORD_1
	v_pk_fma_f32 v[24:25], v[26:27], v[110:111], v[24:25]
	s_nop 0
	v_cvt_pk_f16_f32 v35, v24, v25
	v_lshl_add_u64 v[24:25], s[56:57], 0, v[224:225]
	v_lshl_add_u64 v[28:29], v[24:25], 0, v[220:221]
	v_cvt_f32_f16_e32 v24, v144
	v_cvt_f32_f16_sdwa v25, v144 dst_sel:DWORD dst_unused:UNUSED_PAD src0_sel:WORD_1
	global_store_dwordx4 v[28:29], v[32:35], off
	v_pk_fma_f32 v[20:21], v[20:21], v[96:97], v[24:25]
	s_nop 0
	v_cvt_pk_f16_f32 v24, v20, v21
	v_cvt_f32_f16_e32 v20, v146
	v_cvt_f32_f16_sdwa v21, v146 dst_sel:DWORD dst_unused:UNUSED_PAD src0_sel:WORD_1
	v_pk_fma_f32 v[16:17], v[16:17], v[88:89], v[20:21]
	s_nop 0
	v_cvt_pk_f16_f32 v26, v16, v17
	v_cvt_f32_f16_e32 v16, v145
	v_cvt_f32_f16_sdwa v17, v145 dst_sel:DWORD dst_unused:UNUSED_PAD src0_sel:WORD_1
	v_pk_fma_f32 v[16:17], v[22:23], v[98:99], v[16:17]
	s_nop 0
	v_cvt_pk_f16_f32 v25, v16, v17
	v_cvt_f32_f16_e32 v16, v147
	v_cvt_f32_f16_sdwa v17, v147 dst_sel:DWORD dst_unused:UNUSED_PAD src0_sel:WORD_1
	v_pk_fma_f32 v[16:17], v[18:19], v[90:91], v[16:17]
	s_nop 0
	v_cvt_pk_f16_f32 v27, v16, v17
	v_cvt_f32_f16_e32 v16, v136
	v_cvt_f32_f16_sdwa v17, v136 dst_sel:DWORD dst_unused:UNUSED_PAD src0_sel:WORD_1
	global_store_dwordx4 v[28:29], v[24:27], off offset:256
	v_pk_fma_f32 v[12:13], v[12:13], v[116:117], v[16:17]
	s_nop 0
	v_cvt_pk_f16_f32 v16, v12, v13
	v_cvt_f32_f16_e32 v12, v138
	v_cvt_f32_f16_sdwa v13, v138 dst_sel:DWORD dst_unused:UNUSED_PAD src0_sel:WORD_1
	v_pk_fma_f32 v[8:9], v[8:9], v[108:109], v[12:13]
	s_nop 0
	v_cvt_pk_f16_f32 v18, v8, v9
	v_cvt_f32_f16_e32 v8, v137
	v_cvt_f32_f16_sdwa v9, v137 dst_sel:DWORD dst_unused:UNUSED_PAD src0_sel:WORD_1
	v_pk_fma_f32 v[8:9], v[14:15], v[118:119], v[8:9]
	s_nop 0
	v_cvt_pk_f16_f32 v17, v8, v9
	v_cvt_f32_f16_e32 v8, v139
	v_cvt_f32_f16_sdwa v9, v139 dst_sel:DWORD dst_unused:UNUSED_PAD src0_sel:WORD_1
	v_pk_fma_f32 v[8:9], v[10:11], v[110:111], v[8:9]
	s_nop 0
	v_cvt_pk_f16_f32 v19, v8, v9
	v_lshl_add_u64 v[8:9], s[56:57], 0, v[222:223]
	v_lshl_add_u64 v[12:13], v[8:9], 0, v[220:221]
	v_cvt_f32_f16_e32 v8, v128
	v_cvt_f32_f16_sdwa v9, v128 dst_sel:DWORD dst_unused:UNUSED_PAD src0_sel:WORD_1
	global_store_dwordx4 v[12:13], v[16:19], off
	v_pk_fma_f32 v[4:5], v[4:5], v[96:97], v[8:9]
	s_nop 0
	v_cvt_pk_f16_f32 v8, v4, v5
	v_cvt_f32_f16_e32 v4, v130
	v_cvt_f32_f16_sdwa v5, v130 dst_sel:DWORD dst_unused:UNUSED_PAD src0_sel:WORD_1
	v_pk_fma_f32 v[0:1], v[0:1], v[88:89], v[4:5]
	s_nop 0
	v_cvt_pk_f16_f32 v10, v0, v1
	v_cvt_f32_f16_e32 v0, v129
	v_cvt_f32_f16_sdwa v1, v129 dst_sel:DWORD dst_unused:UNUSED_PAD src0_sel:WORD_1
	v_pk_fma_f32 v[0:1], v[6:7], v[98:99], v[0:1]
	s_nop 0
	v_cvt_pk_f16_f32 v9, v0, v1
	v_cvt_f32_f16_e32 v0, v131
	v_cvt_f32_f16_sdwa v1, v131 dst_sel:DWORD dst_unused:UNUSED_PAD src0_sel:WORD_1
	v_pk_fma_f32 v[0:1], v[2:3], v[90:91], v[0:1]
	s_nop 0
	v_cvt_pk_f16_f32 v11, v0, v1
	global_store_dwordx4 v[12:13], v[8:11], off offset:256
	s_cbranch_vccz .LBB0_1178
	s_waitcnt vmcnt(0)
	s_cmpk_gt_u32 s34, 0xff
	s_cbranch_scc1 .LBB0_1189
	s_barrier
